# hazard-padding parity with the compiler restored (MFMA->load WAW after s_setprio removal, carry pair, readlane->VALU constant); no functional change
# speedup vs baseline: 1.0039x; 1.0038x over previous
; #define UFOR(v, n) _Pragma("unroll") for (int v = 0; v < (n); ++v)
; __device__ __forceinline__ unsigned pk2(float a, float b) { return (unsigned)f2bf(a) | ((unsigned)f2bf(b) << 16); }
; template <int EPI, int K, int KL> ...
;     ...
;   if (EPI == EPI_Z) {
;     u16* dst; int ld, c0;
;     if (bcol < RWC) { dst = e.zrw; ld = RWC; c0 = bcol; } else { dst = e.zcr; ld = CRC; c0 = bcol - RWC; }
;     UFOR(ai, 2) UFOR(bj, 2) UFOR(m, 4) {
;       const f32x4 a = acc[ai][bj][m][0], b = acc[ai][bj][m][1];
;       uint4 pk; pk.x = pk2(a[0], a[1]); pk.y = pk2(a[2], a[3]); pk.z = pk2(b[0], b[1]); pk.w = pk2(b[2], b[3]);
;       *(uint4*)(dst + (size_t)(brow + ai * HALF + wr * 64 + m * 16 + fr) * ld + (c0 + bj * HALF + wc * 32 + fq * 8)) = pk;
;     }
.LBB0_228:
	v_cvt_pk_bf16_f32 v124, v124, v125
	v_cvt_pk_bf16_f32 v125, v126, v127
	v_cvt_pk_bf16_f32 v127, v122, v123
	v_cvt_pk_bf16_f32 v116, v116, v117
	v_cvt_pk_bf16_f32 v117, v118, v119
	v_cvt_pk_bf16_f32 v119, v114, v115
	v_cvt_pk_bf16_f32 v108, v108, v109
	v_cvt_pk_bf16_f32 v109, v110, v111
	v_cvt_pk_bf16_f32 v111, v106, v107
	v_cvt_pk_bf16_f32 v100, v100, v101
	v_cvt_pk_bf16_f32 v101, v102, v103
	v_cvt_pk_bf16_f32 v102, v96, v97
	v_cvt_pk_bf16_f32 v92, v92, v93
	v_cvt_pk_bf16_f32 v93, v94, v95
	v_cvt_pk_bf16_f32 v94, v88, v89
	v_cvt_pk_bf16_f32 v84, v84, v85
	v_cvt_pk_bf16_f32 v85, v86, v87
	v_cvt_pk_bf16_f32 v86, v80, v81
	v_cvt_pk_bf16_f32 v76, v76, v77
	v_cvt_pk_bf16_f32 v77, v78, v79
	v_cvt_pk_bf16_f32 v78, v72, v73
	v_cvt_pk_bf16_f32 v68, v68, v69
	v_cvt_pk_bf16_f32 v69, v70, v71
	v_cvt_pk_bf16_f32 v71, v66, v67
	v_cvt_pk_bf16_f32 v60, v60, v61
	v_cvt_pk_bf16_f32 v61, v62, v63
	v_cvt_pk_bf16_f32 v63, v58, v59
	v_cvt_pk_bf16_f32 v52, v52, v53
	v_cvt_pk_bf16_f32 v53, v54, v55
	v_cvt_pk_bf16_f32 v55, v50, v51
	v_cvt_pk_bf16_f32 v44, v44, v45
	v_cvt_pk_bf16_f32 v45, v46, v47
	v_cvt_pk_bf16_f32 v47, v42, v43
	v_cvt_pk_bf16_f32 v36, v36, v37
	v_cvt_pk_bf16_f32 v37, v38, v39
	v_cvt_pk_bf16_f32 v38, v32, v33
	v_cvt_pk_bf16_f32 v28, v28, v29
	v_cvt_pk_bf16_f32 v29, v30, v31
	v_cvt_pk_bf16_f32 v30, v24, v25
	v_cvt_pk_bf16_f32 v20, v20, v21
	v_cvt_pk_bf16_f32 v21, v22, v23
	v_cvt_pk_bf16_f32 v22, v16, v17
	v_cvt_pk_bf16_f32 v12, v12, v13
	v_cvt_pk_bf16_f32 v13, v14, v15
	v_cvt_pk_bf16_f32 v14, v8, v9
	v_cvt_pk_bf16_f32 v126, v120, v121
	v_cvt_pk_bf16_f32 v118, v112, v113
	v_cvt_pk_bf16_f32 v110, v104, v105
	v_cvt_pk_bf16_f32 v4, v4, v5
	v_cvt_pk_bf16_f32 v5, v6, v7
	v_cvt_pk_bf16_f32 v70, v64, v65
	v_cvt_pk_bf16_f32 v62, v56, v57
	v_cvt_pk_bf16_f32 v54, v48, v49
	v_cvt_pk_bf16_f32 v103, v98, v99
	v_cvt_pk_bf16_f32 v95, v90, v91
	v_cvt_pk_bf16_f32 v87, v82, v83
	v_cvt_pk_bf16_f32 v79, v74, v75
	v_cvt_pk_bf16_f32 v46, v40, v41
	v_cvt_pk_bf16_f32 v39, v34, v35
	v_cvt_pk_bf16_f32 v31, v26, v27
	v_cvt_pk_bf16_f32 v23, v18, v19
	v_cvt_pk_bf16_f32 v15, v10, v11
	v_cvt_pk_bf16_f32 v7, v2, v3
	v_cvt_pk_bf16_f32 v6, v0, v1
	s_add_i32 s15, s46, 0xfffff600
	s_cmp_lt_i32 s14, 10
	s_mov_b32 s18, 0x12d00000
	v_ashrrev_i32_e32 v129, 31, v128
	v_lshl_add_u64 v[130:131], s[44:45], 0, v[132:133]
	s_movk_i32 s14, 0xa00
	s_cselect_b32 s15, s46, s15
	s_cselect_b32 s18, s18, 0x1d000000
	v_lshl_add_u64 v[128:129], v[130:131], 0, v[128:129]
	v_lshlrev_b32_e32 v130, 5, v154
	v_lshlrev_b32_e32 v131, 3, v155
	s_cselect_b32 s14, s14, 0x1200
	s_add_u32 s18, s92, s18
	v_or3_b32 v130, v130, s15, v131
	s_addc_u32 s19, s93, 0
	v_ashrrev_i32_e32 v131, 31, v130
	v_lshl_add_u64 v[130:131], v[130:131], 1, s[18:19]
	v_mad_u64_u32 v[136:137], s[18:19], v128, s14, 0
	v_mov_b32_e32 v128, v137
	v_mad_u64_u32 v[128:129], s[18:19], v129, s14, v[128:129]
	v_mov_b32_e32 v137, v128
	v_lshl_add_u64 v[128:129], v[136:137], 1, v[130:131]
	v_readlane_b32 s18, v254, 59
	v_readlane_b32 s19, v254, 60
	s_lshl_b32 s18, s14, 5
	s_nop 0
	v_lshl_add_u64 v[120:121], v[128:129], 0, s[18:19]
	v_lshl_add_u64 v[112:113], v[120:121], 0, s[18:19]
	v_lshl_add_u64 v[104:105], v[112:113], 0, s[18:19]
	s_mulk_i32 s14, 0xa0
	s_mov_b32 s15, s19
	v_lshl_add_u64 v[64:65], v[104:105], 0, s[14:15]
	v_lshl_add_u64 v[56:57], v[64:65], 0, s[18:19]
	v_lshl_add_u64 v[48:49], v[56:57], 0, s[18:19]
	v_writelane_b32 v254, s14, 59
	v_writelane_b32 v254, s15, 60
	v_lshl_add_u64 v[40:41], v[48:49], 0, s[18:19]
	s_mov_b64 s[50:51], 0
	s_andn2_b64 vcc, exec, s[40:41]
	s_mov_b32 s14, s7
	s_mov_b64 s[44:45], s[42:43]
	global_store_dwordx4 v[128:129], v[124:127], off
	global_store_dwordx4 v[120:121], v[116:119], off
	global_store_dwordx4 v[112:113], v[108:111], off
	global_store_dwordx4 v[104:105], v[100:103], off
	global_store_dwordx4 v[128:129], v[92:95], off offset:256
	global_store_dwordx4 v[120:121], v[84:87], off offset:256
	global_store_dwordx4 v[112:113], v[76:79], off offset:256
	global_store_dwordx4 v[104:105], v[68:71], off offset:256
	global_store_dwordx4 v[64:65], v[60:63], off
	global_store_dwordx4 v[56:57], v[52:55], off
	global_store_dwordx4 v[48:49], v[44:47], off
	global_store_dwordx4 v[40:41], v[36:39], off
	global_store_dwordx4 v[64:65], v[28:31], off offset:256
	global_store_dwordx4 v[56:57], v[20:23], off offset:256
	global_store_dwordx4 v[48:49], v[12:15], off offset:256
	global_store_dwordx4 v[40:41], v[4:7], off offset:256
	s_cbranch_vccz .LBB0_241

; #define STAGE(P, BASE, br, kt) STAGET(tid_, P, BASE, br, kt)
; #define LDA(dst, b, h) UFOR(m, 4) UFOR(k, 2) \
;     dst[m][k] = *reinterpret_cast<const bf16x8*>((char*)SA(b, h) + lds_byte(wr * 64 + m * 16 + fr, k * 32 + fq * 8))
; #define LDB(dst, b, h) UFOR(n, 2) UFOR(k, 2) \
;     dst[n][k] = *reinterpret_cast<const bf16x8*>((char*)SB(b, h) + lds_byte(wc * 32 + n * 16 + fr, k * 32 + fq * 8))
; #define MMA(ai, bj, At, Bq) do { __builtin_amdgcn_s_setprio(1); \
;     UFOR(m, 4) UFOR(n, 2) UFOR(k, 2) \
;       acc[ai][bj][m][n] = __builtin_amdgcn_mfma_f32_16x16x32_bf16(Bq[n][k], At[m][k], acc[ai][bj][m][n], 0, 0, 0); \
;     __builtin_amdgcn_s_setprio(0); } while (0)
; #define WAIT_V(n) asm volatile("s_waitcnt vmcnt(" #n ")" ::: "memory")
; #define WAIT_L(n) asm volatile("s_waitcnt lgkmcnt(" #n ")" ::: "memory")
; #define BAR __builtin_amdgcn_s_barrier()
; #define SCHED __builtin_amdgcn_sched_barrier(0)
; template <int EPI, int K, int KL> ...
;     ...
;   for (int t = 0; t < nt - 2; t += 2) {
;     LDB(B0, 0, 0); SCHED; LDA(At, 0, 0); STAGE(SA(1, 1), A, brow + HALF, t + 1);
;     WAIT_L(8); BAR; WAIT_L(0); MMA(0, 0, At, B0); BAR; SCHED;
;     LDB(B1, 0, 1); STAGE(SB(0, 0), Bt, bcol, t + 2);
;     BAR; WAIT_L(0); MMA(0, 1, At, B1); BAR;
;     LDA(At, 0, 1); STAGE(SA(0, 0), A, brow, t + 2);
;     BAR; WAIT_L(0); MMA(1, 0, At, B0); BAR; SCHED;
;     STAGE(SB(0, 1), Bt, bcol + HALF, t + 2);
;     WAIT_V(6); BAR; MMA(1, 1, At, B1); BAR;
;     LDB(B0, 1, 0); SCHED; LDA(At, 1, 0); STAGE(SA(0, 1), A, brow + HALF, t + 2);
;     WAIT_L(8); BAR; WAIT_L(0); MMA(0, 0, At, B0); BAR; SCHED;
;     LDB(B1, 1, 1); STAGE(SB(1, 0), Bt, bcol, t + 3);
;     BAR; WAIT_L(0); MMA(0, 1, At, B1); BAR;
;     LDA(At, 1, 1); STAGE(SA(1, 0), A, brow, t + 3);
;     BAR; WAIT_L(0); MMA(1, 0, At, B0); BAR; SCHED;
;     STAGE(SB(1, 1), Bt, bcol + HALF, t + 3);
;     WAIT_V(6); BAR; MMA(1, 1, At, B1); BAR;
;   }
;   { LDB(B0, 0, 0); LDA(At, 0, 0); STAGE(SA(1, 1), A, brow + HALF, nt - 1);
;     BAR; WAIT_L(0); MMA(0, 0, At, B0); BAR;
;     LDB(B1, 0, 1); BAR; WAIT_L(0); MMA(0, 1, At, B1); BAR;
;     LDA(At, 0, 1); WAIT_V(4); BAR; WAIT_L(0); MMA(1, 0, At, B0); MMA(1, 1, At, B1); BAR; }
.LBB0_1107:
	ds_read_b128 v[136:139], v171
	ds_read_b128 v[174:177], v171 offset:1024
	ds_read_b128 v[178:181], v171 offset:2048
	ds_read_b128 v[182:185], v171 offset:3072
	v_add_u32_e32 v172, 0xc000, v158
	v_lshl_add_u64 v[214:215], s[92:93], 0, v[148:149]
	v_readfirstlane_b32 s56, v172
	v_lshl_add_u64 v[216:217], v[214:215], 0, s[88:89]
	s_mov_b32 m0, s56
	v_add_u32_e32 v173, 0xe000, v158
	ds_read_b128 v[186:189], v163
	ds_read_b128 v[190:193], v163 offset:1024
	ds_read_b128 v[194:197], v162
	ds_read_b128 v[198:201], v162 offset:1024
	ds_read_b128 v[202:205], v161
	ds_read_b128 v[208:211], v161 offset:1024
	ds_read_b128 v[218:221], v160
	ds_read_b128 v[222:225], v160 offset:1024
	global_load_lds_dwordx4 v[216:217], off
	v_lshl_add_u64 v[216:217], s[92:93], 0, v[150:151]
	v_readfirstlane_b32 s56, v173
	v_lshl_add_u64 v[226:227], v[216:217], 0, s[88:89]
	s_mov_b32 m0, s56
	s_nop 0
	global_load_lds_dwordx4 v[226:227], off
	s_waitcnt lgkmcnt(8)
	s_barrier
	s_waitcnt lgkmcnt(0)
	s_waitcnt lgkmcnt(0)
	v_mfma_f32_16x16x32_bf16 v[0:3], v[136:139], v[186:189], v[0:3]
	v_mfma_f32_16x16x32_bf16 v[4:7], v[178:181], v[186:189], v[4:7]
	v_mfma_f32_16x16x32_bf16 v[8:11], v[136:139], v[194:197], v[8:11]
	v_mfma_f32_16x16x32_bf16 v[16:19], v[178:181], v[194:197], v[16:19]
	v_mfma_f32_16x16x32_bf16 v[28:31], v[136:139], v[202:205], v[28:31]
	v_mfma_f32_16x16x32_bf16 v[40:43], v[178:181], v[202:205], v[40:43]
	v_mfma_f32_16x16x32_bf16 v[52:55], v[136:139], v[218:221], v[52:55]
	v_mfma_f32_16x16x32_bf16 v[64:67], v[178:181], v[218:221], v[64:67]
	v_mfma_f32_16x16x32_bf16 v[0:3], v[174:177], v[190:193], v[0:3]
	v_mfma_f32_16x16x32_bf16 v[4:7], v[182:185], v[190:193], v[4:7]
	v_mfma_f32_16x16x32_bf16 v[8:11], v[174:177], v[198:201], v[8:11]
	v_mfma_f32_16x16x32_bf16 v[16:19], v[182:185], v[198:201], v[16:19]
	v_mfma_f32_16x16x32_bf16 v[28:31], v[174:177], v[208:211], v[28:31]
	v_mfma_f32_16x16x32_bf16 v[40:43], v[182:185], v[208:211], v[40:43]
	v_mfma_f32_16x16x32_bf16 v[52:55], v[174:177], v[222:225], v[52:55]
	v_mfma_f32_16x16x32_bf16 v[64:67], v[182:185], v[222:225], v[64:67]
	s_barrier
	v_lshl_add_u64 v[242:243], s[92:93], 0, v[144:145]
	v_readfirstlane_b32 s56, v157
	v_lshl_add_u64 v[244:245], v[242:243], 0, s[2:3]
	s_mov_b32 m0, s56
	v_add_u32_e32 v134, 0x2000, v157
	ds_read_b128 v[226:229], v169
	ds_read_b128 v[230:233], v169 offset:1024
	ds_read_b128 v[234:237], v169 offset:2048
	ds_read_b128 v[238:241], v169 offset:3072
	global_load_lds_dwordx4 v[244:245], off
	v_lshl_add_u64 v[244:245], s[92:93], 0, v[146:147]
	v_readfirstlane_b32 s56, v134
	v_lshl_add_u64 v[246:247], v[244:245], 0, s[2:3]
	s_mov_b32 m0, s56
	s_nop 0
	global_load_lds_dwordx4 v[246:247], off
	s_barrier
	s_waitcnt lgkmcnt(0)
	s_waitcnt lgkmcnt(0)
	v_mfma_f32_16x16x32_bf16 v[12:15], v[226:229], v[186:189], v[12:15]
	v_mfma_f32_16x16x32_bf16 v[24:27], v[234:237], v[186:189], v[24:27]
	v_mfma_f32_16x16x32_bf16 v[36:39], v[226:229], v[194:197], v[36:39]
	v_mfma_f32_16x16x32_bf16 v[48:51], v[234:237], v[194:197], v[48:51]
	v_mfma_f32_16x16x32_bf16 v[60:63], v[226:229], v[202:205], v[60:63]
	v_mfma_f32_16x16x32_bf16 v[72:75], v[234:237], v[202:205], v[72:75]
	v_mfma_f32_16x16x32_bf16 v[80:83], v[226:229], v[218:221], v[80:83]
	v_mfma_f32_16x16x32_bf16 v[88:91], v[234:237], v[218:221], v[88:91]
	v_mfma_f32_16x16x32_bf16 v[12:15], v[230:233], v[190:193], v[12:15]
	v_mfma_f32_16x16x32_bf16 v[24:27], v[238:241], v[190:193], v[24:27]
	v_mfma_f32_16x16x32_bf16 v[36:39], v[230:233], v[198:201], v[36:39]
	v_mfma_f32_16x16x32_bf16 v[48:51], v[238:241], v[198:201], v[48:51]
	v_mfma_f32_16x16x32_bf16 v[60:63], v[230:233], v[208:211], v[60:63]
	v_mfma_f32_16x16x32_bf16 v[72:75], v[238:241], v[208:211], v[72:75]
	v_mfma_f32_16x16x32_bf16 v[80:83], v[230:233], v[222:225], v[80:83]
	v_mfma_f32_16x16x32_bf16 v[88:91], v[238:241], v[222:225], v[88:91]
	v_readfirstlane_b32 s56, v158
	v_add_u32_e32 v134, 0x2000, v158
	v_lshl_add_u64 v[246:247], v[214:215], 0, s[8:9]
	s_mov_b32 m0, s56
	v_readfirstlane_b32 s56, v134
	s_barrier
	ds_read_b128 v[186:189], v163 offset:16384
	ds_read_b128 v[190:193], v163 offset:17408
	ds_read_b128 v[194:197], v162 offset:16384
	ds_read_b128 v[198:201], v162 offset:17408
	ds_read_b128 v[202:205], v161 offset:16384
	ds_read_b128 v[208:211], v161 offset:17408
	ds_read_b128 v[218:221], v160 offset:16384
	ds_read_b128 v[222:225], v160 offset:17408
	global_load_lds_dwordx4 v[246:247], off
	v_lshl_add_u64 v[246:247], v[216:217], 0, s[8:9]
	s_mov_b32 m0, s56
	s_nop 0
	global_load_lds_dwordx4 v[246:247], off
	s_barrier
	s_waitcnt lgkmcnt(0)
	s_waitcnt lgkmcnt(0)
	v_mfma_f32_16x16x32_bf16 v[20:23], v[136:139], v[186:189], v[20:23]
	v_mfma_f32_16x16x32_bf16 v[32:35], v[178:181], v[186:189], v[32:35]
	v_mfma_f32_16x16x32_bf16 v[44:47], v[136:139], v[194:197], v[44:47]
	v_mfma_f32_16x16x32_bf16 v[56:59], v[178:181], v[194:197], v[56:59]
	v_mfma_f32_16x16x32_bf16 v[68:71], v[136:139], v[202:205], v[68:71]
	v_mfma_f32_16x16x32_bf16 v[76:79], v[178:181], v[202:205], v[76:79]
	v_mfma_f32_16x16x32_bf16 v[84:87], v[136:139], v[218:221], v[84:87]
	v_mfma_f32_16x16x32_bf16 v[92:95], v[178:181], v[218:221], v[92:95]
	v_mfma_f32_16x16x32_bf16 v[20:23], v[174:177], v[190:193], v[20:23]
	v_mfma_f32_16x16x32_bf16 v[32:35], v[182:185], v[190:193], v[32:35]
	v_mfma_f32_16x16x32_bf16 v[44:47], v[174:177], v[198:201], v[44:47]
	v_mfma_f32_16x16x32_bf16 v[56:59], v[182:185], v[198:201], v[56:59]
	v_mfma_f32_16x16x32_bf16 v[68:71], v[174:177], v[208:211], v[68:71]
	v_mfma_f32_16x16x32_bf16 v[76:79], v[182:185], v[208:211], v[76:79]
	v_mfma_f32_16x16x32_bf16 v[84:87], v[174:177], v[222:225], v[84:87]
	v_mfma_f32_16x16x32_bf16 v[92:95], v[182:185], v[222:225], v[92:95]
	s_barrier
; #define STAGE(P, BASE, br, kt) STAGET(tid_, P, BASE, br, kt)
; #define LDA(dst, b, h) UFOR(m, 4) UFOR(k, 2) \
;     dst[m][k] = *reinterpret_cast<const bf16x8*>((char*)SA(b, h) + lds_byte(wr * 64 + m * 16 + fr, k * 32 + fq * 8))
; #define LDB(dst, b, h) UFOR(n, 2) UFOR(k, 2) \
;     dst[n][k] = *reinterpret_cast<const bf16x8*>((char*)SB(b, h) + lds_byte(wc * 32 + n * 16 + fr, k * 32 + fq * 8))
; #define MMA(ai, bj, At, Bq) do { __builtin_amdgcn_s_setprio(1); \
;     UFOR(m, 4) UFOR(n, 2) UFOR(k, 2) \
;       acc[ai][bj][m][n] = __builtin_amdgcn_mfma_f32_16x16x32_bf16(Bq[n][k], At[m][k], acc[ai][bj][m][n], 0, 0, 0); \
;     __builtin_amdgcn_s_setprio(0); } while (0)
; #define WAIT_V(n) asm volatile("s_waitcnt vmcnt(" #n ")" ::: "memory")
; #define WAIT_L(n) asm volatile("s_waitcnt lgkmcnt(" #n ")" ::: "memory")
; #define BAR __builtin_amdgcn_s_barrier()
; #define SCHED __builtin_amdgcn_sched_barrier(0)
; template <int EPI, int K, int KL> ...
;     ...
;   for (int t = 0; t < nt - 2; t += 2) {
;     LDB(B0, 0, 0); SCHED; LDA(At, 0, 0); STAGE(SA(1, 1), A, brow + HALF, t + 1);
;     WAIT_L(8); BAR; WAIT_L(0); MMA(0, 0, At, B0); BAR; SCHED;
;     LDB(B1, 0, 1); STAGE(SB(0, 0), Bt, bcol, t + 2);
;     BAR; WAIT_L(0); MMA(0, 1, At, B1); BAR;
;     LDA(At, 0, 1); STAGE(SA(0, 0), A, brow, t + 2);
;     BAR; WAIT_L(0); MMA(1, 0, At, B0); BAR; SCHED;
;     STAGE(SB(0, 1), Bt, bcol + HALF, t + 2);
;     WAIT_V(6); BAR; MMA(1, 1, At, B1); BAR;
;     LDB(B0, 1, 0); SCHED; LDA(At, 1, 0); STAGE(SA(0, 1), A, brow + HALF, t + 2);
;     WAIT_L(8); BAR; WAIT_L(0); MMA(0, 0, At, B0); BAR; SCHED;
;     LDB(B1, 1, 1); STAGE(SB(1, 0), Bt, bcol, t + 3);
;     BAR; WAIT_L(0); MMA(0, 1, At, B1); BAR;
;     LDA(At, 1, 1); STAGE(SA(1, 0), A, brow, t + 3);
;     BAR; WAIT_L(0); MMA(1, 0, At, B0); BAR; SCHED;
;     STAGE(SB(1, 1), Bt, bcol + HALF, t + 3);
;     WAIT_V(6); BAR; MMA(1, 1, At, B1); BAR;
;   }
;   { LDB(B0, 0, 0); LDA(At, 0, 0); STAGE(SA(1, 1), A, brow + HALF, nt - 1);
;     BAR; WAIT_L(0); MMA(0, 0, At, B0); BAR;
;     LDB(B1, 0, 1); BAR; WAIT_L(0); MMA(0, 1, At, B1); BAR;
;     LDA(At, 0, 1); WAIT_V(4); BAR; WAIT_L(0); MMA(1, 0, At, B0); MMA(1, 1, At, B1); BAR; }
	v_readfirstlane_b32 s56, v159
	v_add_u32_e32 v134, 0x2000, v159
	v_lshl_add_u64 v[136:137], v[242:243], 0, s[96:97]
	s_mov_b32 m0, s56
	v_readfirstlane_b32 s56, v134
	global_load_lds_dwordx4 v[136:137], off
	v_lshl_add_u64 v[136:137], v[244:245], 0, s[96:97]
	s_mov_b32 m0, s56
	s_nop 0
	global_load_lds_dwordx4 v[136:137], off
	s_waitcnt vmcnt(6)
	s_barrier
	v_mfma_f32_16x16x32_bf16 v[96:99], v[226:229], v[186:189], v[96:99]
	v_mfma_f32_16x16x32_bf16 v[100:103], v[234:237], v[186:189], v[100:103]
	v_mfma_f32_16x16x32_bf16 v[104:107], v[226:229], v[194:197], v[104:107]
	v_mfma_f32_16x16x32_bf16 v[108:111], v[234:237], v[194:197], v[108:111]
	v_mfma_f32_16x16x32_bf16 v[112:115], v[226:229], v[202:205], v[112:115]
	v_mfma_f32_16x16x32_bf16 v[116:119], v[234:237], v[202:205], v[116:119]
	v_mfma_f32_16x16x32_bf16 v[120:123], v[226:229], v[218:221], v[120:123]
	v_mfma_f32_16x16x32_bf16 v[124:127], v[234:237], v[218:221], v[124:127]
	v_mfma_f32_16x16x32_bf16 v[96:99], v[230:233], v[190:193], v[96:99]
	v_mfma_f32_16x16x32_bf16 v[100:103], v[238:241], v[190:193], v[100:103]
	v_mfma_f32_16x16x32_bf16 v[104:107], v[230:233], v[198:201], v[104:107]
	v_mfma_f32_16x16x32_bf16 v[108:111], v[238:241], v[198:201], v[108:111]
	v_mfma_f32_16x16x32_bf16 v[112:115], v[230:233], v[208:211], v[112:115]
	v_mfma_f32_16x16x32_bf16 v[116:119], v[238:241], v[208:211], v[116:119]
	v_mfma_f32_16x16x32_bf16 v[120:123], v[230:233], v[222:225], v[120:123]
	v_mfma_f32_16x16x32_bf16 v[124:127], v[238:241], v[222:225], v[124:127]
	s_barrier
	ds_read_b128 v[136:139], v166
	ds_read_b128 v[174:177], v166 offset:1024
	ds_read_b128 v[178:181], v166 offset:2048
	ds_read_b128 v[182:185], v166 offset:3072
	v_add_u32_e32 v134, 0x4000, v158
	v_lshl_add_u64 v[226:227], v[214:215], 0, s[12:13]
	v_readfirstlane_b32 s56, v134
	v_add_u32_e32 v134, 0x6000, v158
	s_mov_b32 m0, s56
	v_readfirstlane_b32 s56, v134
	ds_read_b128 v[186:189], v163 offset:32768
	ds_read_b128 v[190:193], v163 offset:33792
	ds_read_b128 v[194:197], v162 offset:32768
	ds_read_b128 v[198:201], v162 offset:33792
	ds_read_b128 v[202:205], v161 offset:32768
	ds_read_b128 v[208:211], v161 offset:33792
	ds_read_b128 v[218:221], v160 offset:32768
	ds_read_b128 v[222:225], v160 offset:33792
	global_load_lds_dwordx4 v[226:227], off
	v_lshl_add_u64 v[226:227], v[216:217], 0, s[12:13]
	s_mov_b32 m0, s56
	s_nop 0
	global_load_lds_dwordx4 v[226:227], off
	s_waitcnt lgkmcnt(8)
	s_barrier
	s_waitcnt lgkmcnt(0)
	s_waitcnt lgkmcnt(0)
	v_mfma_f32_16x16x32_bf16 v[0:3], v[136:139], v[186:189], v[0:3]
	v_mfma_f32_16x16x32_bf16 v[4:7], v[178:181], v[186:189], v[4:7]
	v_mfma_f32_16x16x32_bf16 v[8:11], v[136:139], v[194:197], v[8:11]
	v_mfma_f32_16x16x32_bf16 v[16:19], v[178:181], v[194:197], v[16:19]
	v_mfma_f32_16x16x32_bf16 v[28:31], v[136:139], v[202:205], v[28:31]
	v_mfma_f32_16x16x32_bf16 v[40:43], v[178:181], v[202:205], v[40:43]
	v_mfma_f32_16x16x32_bf16 v[52:55], v[136:139], v[218:221], v[52:55]
	v_mfma_f32_16x16x32_bf16 v[64:67], v[178:181], v[218:221], v[64:67]
	v_mfma_f32_16x16x32_bf16 v[0:3], v[174:177], v[190:193], v[0:3]
	v_mfma_f32_16x16x32_bf16 v[4:7], v[182:185], v[190:193], v[4:7]
	v_mfma_f32_16x16x32_bf16 v[8:11], v[174:177], v[198:201], v[8:11]
	v_mfma_f32_16x16x32_bf16 v[16:19], v[182:185], v[198:201], v[16:19]
	v_mfma_f32_16x16x32_bf16 v[28:31], v[174:177], v[208:211], v[28:31]
	v_mfma_f32_16x16x32_bf16 v[40:43], v[182:185], v[208:211], v[40:43]
	v_mfma_f32_16x16x32_bf16 v[52:55], v[174:177], v[222:225], v[52:55]
	v_mfma_f32_16x16x32_bf16 v[64:67], v[182:185], v[222:225], v[64:67]
	s_barrier
	v_readfirstlane_b32 s56, v165
	v_add_u32_e32 v134, 0x2000, v165
	v_lshl_add_u64 v[246:247], v[242:243], 0, s[80:81]
	s_mov_b32 m0, s56
	v_readfirstlane_b32 s56, v134
	ds_read_b128 v[226:229], v164
	ds_read_b128 v[230:233], v164 offset:1024
	ds_read_b128 v[234:237], v164 offset:2048
	ds_read_b128 v[238:241], v164 offset:3072
	global_load_lds_dwordx4 v[246:247], off
	v_lshl_add_u64 v[246:247], v[244:245], 0, s[80:81]
	s_mov_b32 m0, s56
	s_nop 0
	global_load_lds_dwordx4 v[246:247], off
	s_barrier
	s_waitcnt lgkmcnt(0)
	s_waitcnt lgkmcnt(0)
	v_mfma_f32_16x16x32_bf16 v[12:15], v[226:229], v[186:189], v[12:15]
	v_mfma_f32_16x16x32_bf16 v[24:27], v[234:237], v[186:189], v[24:27]
	v_mfma_f32_16x16x32_bf16 v[36:39], v[226:229], v[194:197], v[36:39]
	v_mfma_f32_16x16x32_bf16 v[48:51], v[234:237], v[194:197], v[48:51]
	v_mfma_f32_16x16x32_bf16 v[60:63], v[226:229], v[202:205], v[60:63]
	v_mfma_f32_16x16x32_bf16 v[72:75], v[234:237], v[202:205], v[72:75]
	v_mfma_f32_16x16x32_bf16 v[80:83], v[226:229], v[218:221], v[80:83]
	v_mfma_f32_16x16x32_bf16 v[88:91], v[234:237], v[218:221], v[88:91]
	v_mfma_f32_16x16x32_bf16 v[12:15], v[230:233], v[190:193], v[12:15]
	v_mfma_f32_16x16x32_bf16 v[24:27], v[238:241], v[190:193], v[24:27]
	v_mfma_f32_16x16x32_bf16 v[36:39], v[230:233], v[198:201], v[36:39]
	v_mfma_f32_16x16x32_bf16 v[48:51], v[238:241], v[198:201], v[48:51]
	v_mfma_f32_16x16x32_bf16 v[60:63], v[230:233], v[208:211], v[60:63]
	v_mfma_f32_16x16x32_bf16 v[72:75], v[238:241], v[208:211], v[72:75]
	v_mfma_f32_16x16x32_bf16 v[80:83], v[230:233], v[222:225], v[80:83]
	v_mfma_f32_16x16x32_bf16 v[88:91], v[238:241], v[222:225], v[88:91]
	v_readfirstlane_b32 s56, v167
	v_lshl_add_u64 v[214:215], v[214:215], 0, s[16:17]
	s_mov_b32 m0, s56
	v_readfirstlane_b32 s56, v168
	s_barrier
	ds_read_b128 v[186:189], v163 offset:49152
	ds_read_b128 v[190:193], v163 offset:50176
	ds_read_b128 v[194:197], v162 offset:49152
	ds_read_b128 v[198:201], v162 offset:50176
	ds_read_b128 v[202:205], v161 offset:49152
	ds_read_b128 v[208:211], v161 offset:50176
	ds_read_b128 v[218:221], v160 offset:49152
	ds_read_b128 v[222:225], v160 offset:50176
	global_load_lds_dwordx4 v[214:215], off
	v_lshl_add_u64 v[214:215], v[216:217], 0, s[16:17]
	s_mov_b32 m0, s56
	s_nop 0
	global_load_lds_dwordx4 v[214:215], off
	s_barrier
; #define STAGE(P, BASE, br, kt) STAGET(tid_, P, BASE, br, kt)
; #define LDA(dst, b, h) UFOR(m, 4) UFOR(k, 2) \
;     dst[m][k] = *reinterpret_cast<const bf16x8*>((char*)SA(b, h) + lds_byte(wr * 64 + m * 16 + fr, k * 32 + fq * 8))
; #define LDB(dst, b, h) UFOR(n, 2) UFOR(k, 2) \
;     dst[n][k] = *reinterpret_cast<const bf16x8*>((char*)SB(b, h) + lds_byte(wc * 32 + n * 16 + fr, k * 32 + fq * 8))
; #define MMA(ai, bj, At, Bq) do { __builtin_amdgcn_s_setprio(1); \
;     UFOR(m, 4) UFOR(n, 2) UFOR(k, 2) \
;       acc[ai][bj][m][n] = __builtin_amdgcn_mfma_f32_16x16x32_bf16(Bq[n][k], At[m][k], acc[ai][bj][m][n], 0, 0, 0); \
;     __builtin_amdgcn_s_setprio(0); } while (0)
; #define WAIT_V(n) asm volatile("s_waitcnt vmcnt(" #n ")" ::: "memory")
; #define WAIT_L(n) asm volatile("s_waitcnt lgkmcnt(" #n ")" ::: "memory")
; #define BAR __builtin_amdgcn_s_barrier()
; #define SCHED __builtin_amdgcn_sched_barrier(0)
; template <int EPI, int K, int KL> ...
;     ...
;   for (int t = 0; t < nt - 2; t += 2) {
;     LDB(B0, 0, 0); SCHED; LDA(At, 0, 0); STAGE(SA(1, 1), A, brow + HALF, t + 1);
;     WAIT_L(8); BAR; WAIT_L(0); MMA(0, 0, At, B0); BAR; SCHED;
;     LDB(B1, 0, 1); STAGE(SB(0, 0), Bt, bcol, t + 2);
;     BAR; WAIT_L(0); MMA(0, 1, At, B1); BAR;
;     LDA(At, 0, 1); STAGE(SA(0, 0), A, brow, t + 2);
;     BAR; WAIT_L(0); MMA(1, 0, At, B0); BAR; SCHED;
;     STAGE(SB(0, 1), Bt, bcol + HALF, t + 2);
;     WAIT_V(6); BAR; MMA(1, 1, At, B1); BAR;
;     LDB(B0, 1, 0); SCHED; LDA(At, 1, 0); STAGE(SA(0, 1), A, brow + HALF, t + 2);
;     WAIT_L(8); BAR; WAIT_L(0); MMA(0, 0, At, B0); BAR; SCHED;
;     LDB(B1, 1, 1); STAGE(SB(1, 0), Bt, bcol, t + 3);
;     BAR; WAIT_L(0); MMA(0, 1, At, B1); BAR;
;     LDA(At, 1, 1); STAGE(SA(1, 0), A, brow, t + 3);
;     BAR; WAIT_L(0); MMA(1, 0, At, B0); BAR; SCHED;
;     STAGE(SB(1, 1), Bt, bcol + HALF, t + 3);
;     WAIT_V(6); BAR; MMA(1, 1, At, B1); BAR;
;   }
;   { LDB(B0, 0, 0); LDA(At, 0, 0); STAGE(SA(1, 1), A, brow + HALF, nt - 1);
;     BAR; WAIT_L(0); MMA(0, 0, At, B0); BAR;
;     LDB(B1, 0, 1); BAR; WAIT_L(0); MMA(0, 1, At, B1); BAR;
;     LDA(At, 0, 1); WAIT_V(4); BAR; WAIT_L(0); MMA(1, 0, At, B0); MMA(1, 1, At, B1); BAR; }
	s_waitcnt lgkmcnt(0)
	s_waitcnt lgkmcnt(0)
	v_mfma_f32_16x16x32_bf16 v[20:23], v[136:139], v[186:189], v[20:23]
	v_mfma_f32_16x16x32_bf16 v[32:35], v[178:181], v[186:189], v[32:35]
	v_mfma_f32_16x16x32_bf16 v[44:47], v[136:139], v[194:197], v[44:47]
	v_mfma_f32_16x16x32_bf16 v[56:59], v[178:181], v[194:197], v[56:59]
	v_mfma_f32_16x16x32_bf16 v[68:71], v[136:139], v[202:205], v[68:71]
	v_mfma_f32_16x16x32_bf16 v[76:79], v[178:181], v[202:205], v[76:79]
	v_mfma_f32_16x16x32_bf16 v[84:87], v[136:139], v[218:221], v[84:87]
	v_mfma_f32_16x16x32_bf16 v[92:95], v[178:181], v[218:221], v[92:95]
	v_mfma_f32_16x16x32_bf16 v[20:23], v[174:177], v[190:193], v[20:23]
	v_mfma_f32_16x16x32_bf16 v[32:35], v[182:185], v[190:193], v[32:35]
	v_mfma_f32_16x16x32_bf16 v[44:47], v[174:177], v[198:201], v[44:47]
	v_mfma_f32_16x16x32_bf16 v[56:59], v[182:185], v[198:201], v[56:59]
	v_mfma_f32_16x16x32_bf16 v[68:71], v[174:177], v[208:211], v[68:71]
	v_mfma_f32_16x16x32_bf16 v[76:79], v[182:185], v[208:211], v[76:79]
	v_mfma_f32_16x16x32_bf16 v[84:87], v[174:177], v[222:225], v[84:87]
	v_mfma_f32_16x16x32_bf16 v[92:95], v[182:185], v[222:225], v[92:95]
	s_barrier
	v_readfirstlane_b32 s56, v170
	v_add_u32_e32 v134, 0x2000, v170
	v_lshl_add_u64 v[136:137], v[242:243], 0, s[90:91]
	s_mov_b32 m0, s56
	v_readfirstlane_b32 s56, v134
	global_load_lds_dwordx4 v[136:137], off
	v_lshl_add_u64 v[136:137], v[244:245], 0, s[90:91]
	s_mov_b32 m0, s56
	s_nop 0
	global_load_lds_dwordx4 v[136:137], off
	s_waitcnt vmcnt(6)
	s_barrier
	v_mfma_f32_16x16x32_bf16 v[96:99], v[226:229], v[186:189], v[96:99]
	v_mfma_f32_16x16x32_bf16 v[100:103], v[234:237], v[186:189], v[100:103]
	v_mfma_f32_16x16x32_bf16 v[104:107], v[226:229], v[194:197], v[104:107]
	v_mfma_f32_16x16x32_bf16 v[108:111], v[234:237], v[194:197], v[108:111]
	v_mfma_f32_16x16x32_bf16 v[112:115], v[226:229], v[202:205], v[112:115]
	v_mfma_f32_16x16x32_bf16 v[116:119], v[234:237], v[202:205], v[116:119]
	v_mfma_f32_16x16x32_bf16 v[120:123], v[226:229], v[218:221], v[120:123]
	v_mfma_f32_16x16x32_bf16 v[124:127], v[234:237], v[218:221], v[124:127]
	v_mfma_f32_16x16x32_bf16 v[96:99], v[230:233], v[190:193], v[96:99]
	v_mfma_f32_16x16x32_bf16 v[100:103], v[238:241], v[190:193], v[100:103]
	v_mfma_f32_16x16x32_bf16 v[104:107], v[230:233], v[198:201], v[104:107]
	v_mfma_f32_16x16x32_bf16 v[108:111], v[238:241], v[198:201], v[108:111]
	v_mfma_f32_16x16x32_bf16 v[112:115], v[230:233], v[208:211], v[112:115]
	v_mfma_f32_16x16x32_bf16 v[116:119], v[238:241], v[208:211], v[116:119]
	v_mfma_f32_16x16x32_bf16 v[120:123], v[230:233], v[222:225], v[120:123]
	v_mfma_f32_16x16x32_bf16 v[124:127], v[238:241], v[222:225], v[124:127]
	s_add_i32 s53, s53, 2
	v_lshl_add_u64 v[144:145], v[144:145], 0, s[20:21]
	v_lshl_add_u64 v[146:147], v[146:147], 0, s[20:21]
	v_lshl_add_u64 v[148:149], v[148:149], 0, s[20:21]
	s_cmp_lt_u32 s53, 28
	v_lshl_add_u64 v[150:151], v[150:151], 0, s[20:21]
	s_barrier
	s_cbranch_scc1 .LBB0_1107
	s_add_u32 s40, s40, 0x80f80
	s_addc_u32 s41, s41, 0
	v_lshl_add_u64 v[130:131], s[40:41], 0, v[130:131]
	v_readfirstlane_b32 s53, v172
	v_lshl_add_u64 v[128:129], v[128:129], 1, v[130:131]
	s_mov_b32 m0, s53
	ds_read_b128 v[136:139], v171
	ds_read_b128 v[144:147], v171 offset:1024
	ds_read_b128 v[148:151], v171 offset:2048
	ds_read_b128 v[174:177], v171 offset:3072
	ds_read_b128 v[178:181], v163
	ds_read_b128 v[182:185], v163 offset:1024
	ds_read_b128 v[186:189], v162
	ds_read_b128 v[190:193], v162 offset:1024
	ds_read_b128 v[194:197], v161
	ds_read_b128 v[198:201], v161 offset:1024
	ds_read_b128 v[202:205], v160
	ds_read_b128 v[208:211], v160 offset:1024
	global_load_lds_dwordx4 v[128:129], off
	v_lshl_add_u64 v[128:129], s[40:41], 0, v[142:143]
	v_readfirstlane_b32 s40, v173
	v_lshl_add_u64 v[128:129], v[140:141], 1, v[128:129]
	s_mov_b32 m0, s40
	s_nop 0
	global_load_lds_dwordx4 v[128:129], off
	s_barrier
	s_waitcnt lgkmcnt(0)
	s_waitcnt lgkmcnt(0)
	v_mfma_f32_16x16x32_bf16 v[0:3], v[136:139], v[178:181], v[0:3]
	v_mfma_f32_16x16x32_bf16 v[4:7], v[148:151], v[178:181], v[4:7]
	v_mfma_f32_16x16x32_bf16 v[8:11], v[136:139], v[186:189], v[8:11]
	v_mfma_f32_16x16x32_bf16 v[16:19], v[148:151], v[186:189], v[16:19]
	v_mfma_f32_16x16x32_bf16 v[28:31], v[136:139], v[194:197], v[28:31]
	v_mfma_f32_16x16x32_bf16 v[40:43], v[148:151], v[194:197], v[40:43]
	v_mfma_f32_16x16x32_bf16 v[52:55], v[136:139], v[202:205], v[52:55]
	v_mfma_f32_16x16x32_bf16 v[64:67], v[148:151], v[202:205], v[64:67]
	v_mfma_f32_16x16x32_bf16 v[0:3], v[144:147], v[182:185], v[0:3]
	v_mfma_f32_16x16x32_bf16 v[4:7], v[174:177], v[182:185], v[4:7]
	v_mfma_f32_16x16x32_bf16 v[8:11], v[144:147], v[190:193], v[8:11]
	v_mfma_f32_16x16x32_bf16 v[16:19], v[174:177], v[190:193], v[16:19]
	v_mfma_f32_16x16x32_bf16 v[28:31], v[144:147], v[198:201], v[28:31]
	v_mfma_f32_16x16x32_bf16 v[40:43], v[174:177], v[198:201], v[40:43]
	v_mfma_f32_16x16x32_bf16 v[52:55], v[144:147], v[208:211], v[52:55]
	v_mfma_f32_16x16x32_bf16 v[64:67], v[174:177], v[208:211], v[64:67]
	s_barrier
	ds_read_b128 v[128:131], v169
	ds_read_b128 v[140:143], v169 offset:1024
	ds_read_b128 v[170:173], v169 offset:2048
	ds_read_b128 v[218:221], v169 offset:3072
	s_barrier
; #define STAGE(P, BASE, br, kt) STAGET(tid_, P, BASE, br, kt)
; #define LDA(dst, b, h) UFOR(m, 4) UFOR(k, 2) \
;     dst[m][k] = *reinterpret_cast<const bf16x8*>((char*)SA(b, h) + lds_byte(wr * 64 + m * 16 + fr, k * 32 + fq * 8))
; #define LDB(dst, b, h) UFOR(n, 2) UFOR(k, 2) \
;     dst[n][k] = *reinterpret_cast<const bf16x8*>((char*)SB(b, h) + lds_byte(wc * 32 + n * 16 + fr, k * 32 + fq * 8))
; #define MMA(ai, bj, At, Bq) do { __builtin_amdgcn_s_setprio(1); \
;     UFOR(m, 4) UFOR(n, 2) UFOR(k, 2) \
;       acc[ai][bj][m][n] = __builtin_amdgcn_mfma_f32_16x16x32_bf16(Bq[n][k], At[m][k], acc[ai][bj][m][n], 0, 0, 0); \
;     __builtin_amdgcn_s_setprio(0); } while (0)
; #define WAIT_V(n) asm volatile("s_waitcnt vmcnt(" #n ")" ::: "memory")
; #define WAIT_L(n) asm volatile("s_waitcnt lgkmcnt(" #n ")" ::: "memory")
; #define BAR __builtin_amdgcn_s_barrier()
; template <int EPI, int K, int KL> ...
;     ...
;   { LDB(B0, 0, 0); LDA(At, 0, 0); STAGE(SA(1, 1), A, brow + HALF, nt - 1);
;     BAR; WAIT_L(0); MMA(0, 0, At, B0); BAR;
;     LDB(B1, 0, 1); BAR; WAIT_L(0); MMA(0, 1, At, B1); BAR;
;     LDA(At, 0, 1); WAIT_V(4); BAR; WAIT_L(0); MMA(1, 0, At, B0); MMA(1, 1, At, B1); BAR; }
;   { LDB(B0, 1, 0); LDA(At, 1, 0); WAIT_V(2); BAR; WAIT_L(0); MMA(0, 0, At, B0); BAR;
;     LDB(B1, 1, 1); WAIT_V(0); BAR; WAIT_L(0); MMA(0, 1, At, B1); BAR;
;     LDA(At, 1, 1); BAR; WAIT_L(0); MMA(1, 0, At, B0); MMA(1, 1, At, B1); BAR; }
;   if (wr == 0) BAR;
	s_waitcnt lgkmcnt(0)
	s_waitcnt lgkmcnt(0)
	v_mfma_f32_16x16x32_bf16 v[12:15], v[128:131], v[178:181], v[12:15]
	v_mfma_f32_16x16x32_bf16 v[24:27], v[170:173], v[178:181], v[24:27]
	v_mfma_f32_16x16x32_bf16 v[36:39], v[128:131], v[186:189], v[36:39]
	v_mfma_f32_16x16x32_bf16 v[48:51], v[170:173], v[186:189], v[48:51]
	v_mfma_f32_16x16x32_bf16 v[60:63], v[128:131], v[194:197], v[60:63]
	v_mfma_f32_16x16x32_bf16 v[72:75], v[170:173], v[194:197], v[72:75]
	v_mfma_f32_16x16x32_bf16 v[80:83], v[128:131], v[202:205], v[80:83]
	v_mfma_f32_16x16x32_bf16 v[12:15], v[140:143], v[182:185], v[12:15]
	v_mfma_f32_16x16x32_bf16 v[24:27], v[218:221], v[182:185], v[24:27]
	v_mfma_f32_16x16x32_bf16 v[36:39], v[140:143], v[190:193], v[36:39]
	v_mfma_f32_16x16x32_bf16 v[48:51], v[218:221], v[190:193], v[48:51]
	v_mfma_f32_16x16x32_bf16 v[60:63], v[140:143], v[198:201], v[60:63]
	v_mfma_f32_16x16x32_bf16 v[72:75], v[218:221], v[198:201], v[72:75]
	v_mfma_f32_16x16x32_bf16 v[178:181], v[140:143], v[208:211], v[80:83]
	v_mfma_f32_16x16x32_bf16 v[80:83], v[170:173], v[202:205], v[88:91]
	v_mfma_f32_16x16x32_bf16 v[182:185], v[218:221], v[208:211], v[80:83]
	s_barrier
	s_nop 5
	ds_read_b128 v[80:83], v163 offset:16384
	ds_read_b128 v[88:91], v163 offset:17408
	ds_read_b128 v[186:189], v162 offset:16384
	ds_read_b128 v[190:193], v162 offset:17408
	ds_read_b128 v[194:197], v161 offset:16384
	ds_read_b128 v[198:201], v161 offset:17408
	ds_read_b128 v[202:205], v160 offset:16384
	ds_read_b128 v[208:211], v160 offset:17408
	s_waitcnt vmcnt(4)
	s_barrier
	s_waitcnt lgkmcnt(0)
	s_waitcnt lgkmcnt(0)
	v_mfma_f32_16x16x32_bf16 v[56:59], v[148:151], v[186:189], v[56:59]
	v_mfma_f32_16x16x32_bf16 v[222:225], v[174:177], v[190:193], v[56:59]
	v_mfma_f32_16x16x32_bf16 v[56:59], v[136:139], v[194:197], v[68:71]
	v_mfma_f32_16x16x32_bf16 v[226:229], v[144:147], v[198:201], v[56:59]
	v_mfma_f32_16x16x32_bf16 v[56:59], v[148:151], v[194:197], v[76:79]
	v_mfma_f32_16x16x32_bf16 v[20:23], v[136:139], v[80:83], v[20:23]
	v_mfma_f32_16x16x32_bf16 v[32:35], v[148:151], v[80:83], v[32:35]
	v_mfma_f32_16x16x32_bf16 v[44:47], v[136:139], v[186:189], v[44:47]
	v_mfma_f32_16x16x32_bf16 v[230:233], v[174:177], v[198:201], v[56:59]
	v_mfma_f32_16x16x32_bf16 v[56:59], v[136:139], v[202:205], v[84:87]
	v_mfma_f32_16x16x32_bf16 v[20:23], v[144:147], v[88:91], v[20:23]
	v_mfma_f32_16x16x32_bf16 v[32:35], v[174:177], v[88:91], v[32:35]
	v_mfma_f32_16x16x32_bf16 v[44:47], v[144:147], v[190:193], v[44:47]
	v_mfma_f32_16x16x32_bf16 v[136:139], v[144:147], v[208:211], v[56:59]
	v_mfma_f32_16x16x32_bf16 v[56:59], v[148:151], v[202:205], v[92:95]
	v_mfma_f32_16x16x32_bf16 v[144:147], v[174:177], v[208:211], v[56:59]
	v_mfma_f32_16x16x32_bf16 v[56:59], v[128:131], v[80:83], v[96:99]
	v_mfma_f32_16x16x32_bf16 v[148:151], v[140:143], v[88:91], v[56:59]
	v_mfma_f32_16x16x32_bf16 v[56:59], v[170:173], v[80:83], v[100:103]
	v_mfma_f32_16x16x32_bf16 v[174:177], v[218:221], v[88:91], v[56:59]
	v_mfma_f32_16x16x32_bf16 v[56:59], v[128:131], v[186:189], v[104:107]
	v_mfma_f32_16x16x32_bf16 v[234:237], v[140:143], v[190:193], v[56:59]
	v_mfma_f32_16x16x32_bf16 v[56:59], v[170:173], v[186:189], v[108:111]
	v_mfma_f32_16x16x32_bf16 v[186:189], v[218:221], v[190:193], v[56:59]
	v_mfma_f32_16x16x32_bf16 v[56:59], v[128:131], v[194:197], v[112:115]
	v_mfma_f32_16x16x32_bf16 v[190:193], v[140:143], v[198:201], v[56:59]
	v_mfma_f32_16x16x32_bf16 v[56:59], v[170:173], v[194:197], v[116:119]
	v_mfma_f32_16x16x32_bf16 v[194:197], v[218:221], v[198:201], v[56:59]
	v_mfma_f32_16x16x32_bf16 v[56:59], v[128:131], v[202:205], v[120:123]
	v_mfma_f32_16x16x32_bf16 v[128:131], v[140:143], v[208:211], v[56:59]
	v_mfma_f32_16x16x32_bf16 v[56:59], v[170:173], v[202:205], v[124:127]
	v_mfma_f32_16x16x32_bf16 v[140:143], v[218:221], v[208:211], v[56:59]
	s_barrier
	ds_read_b128 v[168:171], v166
	ds_read_b128 v[198:201], v166 offset:1024
	ds_read_b128 v[202:205], v166 offset:2048
	ds_read_b128 v[208:211], v166 offset:3072
	s_nop 1
	ds_read_b128 v[56:59], v163 offset:32768
	ds_read_b128 v[68:71], v163 offset:33792
	ds_read_b128 v[76:79], v162 offset:32768
	ds_read_b128 v[80:83], v162 offset:33792
	ds_read_b128 v[218:221], v161 offset:32768
	ds_read_b128 v[238:241], v161 offset:33792
	ds_read_b128 v[242:245], v160 offset:32768
	ds_read_b128 v[246:249], v160 offset:33792
	s_waitcnt vmcnt(2)
	s_barrier
; #define STAGE(P, BASE, br, kt) STAGET(tid_, P, BASE, br, kt)
; #define LDA(dst, b, h) UFOR(m, 4) UFOR(k, 2) \
;     dst[m][k] = *reinterpret_cast<const bf16x8*>((char*)SA(b, h) + lds_byte(wr * 64 + m * 16 + fr, k * 32 + fq * 8))
; #define LDB(dst, b, h) UFOR(n, 2) UFOR(k, 2) \
;     dst[n][k] = *reinterpret_cast<const bf16x8*>((char*)SB(b, h) + lds_byte(wc * 32 + n * 16 + fr, k * 32 + fq * 8))
; #define MMA(ai, bj, At, Bq) do { __builtin_amdgcn_s_setprio(1); \
;     UFOR(m, 4) UFOR(n, 2) UFOR(k, 2) \
;       acc[ai][bj][m][n] = __builtin_amdgcn_mfma_f32_16x16x32_bf16(Bq[n][k], At[m][k], acc[ai][bj][m][n], 0, 0, 0); \
;     __builtin_amdgcn_s_setprio(0); } while (0)
; #define WAIT_V(n) asm volatile("s_waitcnt vmcnt(" #n ")" ::: "memory")
; #define WAIT_L(n) asm volatile("s_waitcnt lgkmcnt(" #n ")" ::: "memory")
; #define BAR __builtin_amdgcn_s_barrier()
; template <int EPI, int K, int KL> ...
;     ...
;   { LDB(B0, 0, 0); LDA(At, 0, 0); STAGE(SA(1, 1), A, brow + HALF, nt - 1);
;     BAR; WAIT_L(0); MMA(0, 0, At, B0); BAR;
;     LDB(B1, 0, 1); BAR; WAIT_L(0); MMA(0, 1, At, B1); BAR;
;     LDA(At, 0, 1); WAIT_V(4); BAR; WAIT_L(0); MMA(1, 0, At, B0); MMA(1, 1, At, B1); BAR; }
;   { LDB(B0, 1, 0); LDA(At, 1, 0); WAIT_V(2); BAR; WAIT_L(0); MMA(0, 0, At, B0); BAR;
;     LDB(B1, 1, 1); WAIT_V(0); BAR; WAIT_L(0); MMA(0, 1, At, B1); BAR;
;     LDA(At, 1, 1); BAR; WAIT_L(0); MMA(1, 0, At, B0); MMA(1, 1, At, B1); BAR; }
;   if (wr == 0) BAR;
	s_waitcnt lgkmcnt(0)
	s_waitcnt lgkmcnt(0)
	v_mfma_f32_16x16x32_bf16 v[0:3], v[168:171], v[56:59], v[0:3]
	v_mfma_f32_16x16x32_bf16 v[124:127], v[198:201], v[68:71], v[0:3]
	v_mfma_f32_16x16x32_bf16 v[0:3], v[202:205], v[56:59], v[4:7]
	v_mfma_f32_16x16x32_bf16 v[120:123], v[208:211], v[68:71], v[0:3]
	v_mfma_f32_16x16x32_bf16 v[0:3], v[168:171], v[76:79], v[8:11]
	v_mfma_f32_16x16x32_bf16 v[116:119], v[198:201], v[80:83], v[0:3]
	v_mfma_f32_16x16x32_bf16 v[0:3], v[202:205], v[76:79], v[16:19]
	v_mfma_f32_16x16x32_bf16 v[112:115], v[208:211], v[80:83], v[0:3]
	v_mfma_f32_16x16x32_bf16 v[0:3], v[168:171], v[218:221], v[28:31]
	v_mfma_f32_16x16x32_bf16 v[108:111], v[198:201], v[238:241], v[0:3]
	v_mfma_f32_16x16x32_bf16 v[0:3], v[202:205], v[218:221], v[40:43]
	v_mfma_f32_16x16x32_bf16 v[104:107], v[208:211], v[238:241], v[0:3]
	v_mfma_f32_16x16x32_bf16 v[0:3], v[168:171], v[242:245], v[52:55]
	v_mfma_f32_16x16x32_bf16 v[100:103], v[198:201], v[246:249], v[0:3]
	v_mfma_f32_16x16x32_bf16 v[0:3], v[202:205], v[242:245], v[64:67]
	v_mfma_f32_16x16x32_bf16 v[96:99], v[208:211], v[246:249], v[0:3]
	s_barrier
	s_nop 5
	ds_read_b128 v[0:3], v164
	ds_read_b128 v[4:7], v164 offset:1024
	ds_read_b128 v[214:217], v164 offset:2048
	ds_read_b128 v[164:167], v164 offset:3072
	s_waitcnt vmcnt(0)
	s_barrier
	s_waitcnt lgkmcnt(0)
	s_waitcnt lgkmcnt(0)
	v_mfma_f32_16x16x32_bf16 v[8:11], v[0:3], v[56:59], v[12:15]
	v_mfma_f32_16x16x32_bf16 v[92:95], v[4:7], v[68:71], v[8:11]
	v_mfma_f32_16x16x32_bf16 v[8:11], v[214:217], v[56:59], v[24:27]
	v_mfma_f32_16x16x32_bf16 v[88:91], v[164:167], v[68:71], v[8:11]
	v_mfma_f32_16x16x32_bf16 v[8:11], v[0:3], v[76:79], v[36:39]
	v_mfma_f32_16x16x32_bf16 v[84:87], v[4:7], v[80:83], v[8:11]
	v_mfma_f32_16x16x32_bf16 v[8:11], v[214:217], v[76:79], v[48:51]
	v_mfma_f32_16x16x32_bf16 v[80:83], v[164:167], v[80:83], v[8:11]
	v_mfma_f32_16x16x32_bf16 v[8:11], v[0:3], v[218:221], v[60:63]
	v_mfma_f32_16x16x32_bf16 v[76:79], v[4:7], v[238:241], v[8:11]
	v_mfma_f32_16x16x32_bf16 v[8:11], v[214:217], v[218:221], v[72:75]
	v_mfma_f32_16x16x32_bf16 v[72:75], v[164:167], v[238:241], v[8:11]
	v_mfma_f32_16x16x32_bf16 v[8:11], v[0:3], v[242:245], v[178:181]
	v_mfma_f32_16x16x32_bf16 v[68:71], v[4:7], v[246:249], v[8:11]
	v_mfma_f32_16x16x32_bf16 v[8:11], v[214:217], v[242:245], v[182:185]
	v_mfma_f32_16x16x32_bf16 v[64:67], v[164:167], v[246:249], v[8:11]
	s_barrier
	s_nop 5
	ds_read_b128 v[8:11], v163 offset:49152
	ds_read_b128 v[12:15], v163 offset:50176
	ds_read_b128 v[16:19], v162 offset:49152
	ds_read_b128 v[178:181], v162 offset:50176
	ds_read_b128 v[182:185], v161 offset:49152
	ds_read_b128 v[218:221], v161 offset:50176
	ds_read_b128 v[238:241], v160 offset:49152
	ds_read_b128 v[158:161], v160 offset:50176
	s_barrier
	s_waitcnt lgkmcnt(0)
	s_waitcnt lgkmcnt(0)
	v_mfma_f32_16x16x32_bf16 v[20:23], v[168:171], v[8:11], v[20:23]
	v_mfma_f32_16x16x32_bf16 v[60:63], v[198:201], v[12:15], v[20:23]
	v_mfma_f32_16x16x32_bf16 v[20:23], v[202:205], v[8:11], v[32:35]
	v_mfma_f32_16x16x32_bf16 v[56:59], v[208:211], v[12:15], v[20:23]
	v_mfma_f32_16x16x32_bf16 v[20:23], v[168:171], v[16:19], v[44:47]
	v_mfma_f32_16x16x32_bf16 v[52:55], v[198:201], v[178:181], v[20:23]
	v_mfma_f32_16x16x32_bf16 v[20:23], v[202:205], v[16:19], v[222:225]
	v_mfma_f32_16x16x32_bf16 v[48:51], v[208:211], v[178:181], v[20:23]
	v_mfma_f32_16x16x32_bf16 v[20:23], v[168:171], v[182:185], v[226:229]
	v_mfma_f32_16x16x32_bf16 v[44:47], v[198:201], v[218:221], v[20:23]
	v_mfma_f32_16x16x32_bf16 v[20:23], v[202:205], v[182:185], v[230:233]
	v_mfma_f32_16x16x32_bf16 v[40:43], v[208:211], v[218:221], v[20:23]
	v_mfma_f32_16x16x32_bf16 v[20:23], v[168:171], v[238:241], v[136:139]
	v_mfma_f32_16x16x32_bf16 v[36:39], v[198:201], v[158:161], v[20:23]
	v_mfma_f32_16x16x32_bf16 v[20:23], v[202:205], v[238:241], v[144:147]
	v_mfma_f32_16x16x32_bf16 v[32:35], v[208:211], v[158:161], v[20:23]
	v_mfma_f32_16x16x32_bf16 v[20:23], v[0:3], v[8:11], v[148:151]
	v_mfma_f32_16x16x32_bf16 v[8:11], v[214:217], v[8:11], v[174:177]
	v_mfma_f32_16x16x32_bf16 v[24:27], v[164:167], v[12:15], v[8:11]
	v_mfma_f32_16x16x32_bf16 v[8:11], v[0:3], v[16:19], v[234:237]
	v_mfma_f32_16x16x32_bf16 v[28:31], v[4:7], v[12:15], v[20:23]
	v_mfma_f32_16x16x32_bf16 v[20:23], v[4:7], v[178:181], v[8:11]
	v_mfma_f32_16x16x32_bf16 v[8:11], v[214:217], v[16:19], v[186:189]
	v_mfma_f32_16x16x32_bf16 v[16:19], v[164:167], v[178:181], v[8:11]
	v_mfma_f32_16x16x32_bf16 v[8:11], v[0:3], v[182:185], v[190:193]
	v_mfma_f32_16x16x32_bf16 v[0:3], v[0:3], v[238:241], v[128:131]
	v_mfma_f32_16x16x32_bf16 v[12:15], v[4:7], v[218:221], v[8:11]
	v_mfma_f32_16x16x32_bf16 v[8:11], v[214:217], v[182:185], v[194:197]
	v_mfma_f32_16x16x32_bf16 v[4:7], v[4:7], v[158:161], v[0:3]
	v_mfma_f32_16x16x32_bf16 v[0:3], v[214:217], v[238:241], v[140:143]
	v_mfma_f32_16x16x32_bf16 v[8:11], v[164:167], v[218:221], v[8:11]
	v_mfma_f32_16x16x32_bf16 v[0:3], v[164:167], v[158:161], v[0:3]
	s_movk_i32 s40, 0x100
	v_cmp_gt_u32_e32 vcc, s40, v152
	s_barrier
	s_and_saveexec_b64 s[40:41], vcc
	s_cbranch_execz .LBB0_1110
	s_barrier

; #define UFOR(v, n) _Pragma("unroll") for (int v = 0; v < (n); ++v)
; __device__ __forceinline__ unsigned pk2(float a, float b) { return (unsigned)f2bf(a) | ((unsigned)f2bf(b) << 16); }
; __device__ __forceinline__ float lo2f(unsigned u) { return __uint_as_float(u << 16); }
; __device__ __forceinline__ float hi2f(unsigned u) { return __uint_as_float(u & 0xffff0000u); }
; __device__ __forceinline__ float siluf_(float x) { return x / (1.f + __expf(-x)); }
; template <int EPI, int K, int KL> ...
;     ...
;       for (int q = 0; q < 16; ++q) {
;         const int lr = lr0 + q;
;         const int lrn = lr < 255 ? lr + 1 : 255;
;         const uint2 a = *(const uint2*)(U + lrn * 256 + c4), b = *(const uint2*)(U + lrn * 256 + 128 + c4);
;         ng[0] = lo2f(a.x); ng[1] = hi2f(a.x); ng[2] = lo2f(a.y); ng[3] = hi2f(a.y);
;         nv[0] = lo2f(b.x); nv[1] = hi2f(b.x); nv[2] = lo2f(b.y); nv[3] = hi2f(b.y);
;         const long gr = brow + lr;
;         const bool valid = (gr >= seq0) && (gr < seq1) && (lr >= 1 || gr == seq0) && (lr <= 254 || gr == seq1 - 1);
;         if (valid) {
;           const float mp = (gr - 1 >= seq0) ? 1.f : 0.f, mn = (gr + 1 < seq1) ? 1.f : 0.f;
;           float o[4];
;           UFOR(x, 4) {
;             const float g = wg[x][0] * pg[x] * mp + wg[x][1] * cgv[x] + wg[x][2] * ng[x] * mn;
;             const float v = wv[x][0] * pvv[x] * mp + wv[x][1] * cv[x] + wv[x][2] * nv[x] * mn;
;             o[x] = siluf_(g) * v;
;           }
;           uint2 pk; pk.x = pk2(o[0], o[1]); pk.y = pk2(o[2], o[3]);
;           *(uint2*)(e.h2 + (size_t)gr * DFF + gc) = pk;
;         }
.LBB0_1112:
	v_lshl_add_u64 v[52:53], v[132:133], 0, s[58:59]
	v_min_i32_e32 v36, 0xfe, v52
	v_lshl_add_u32 v36, v36, 9, v64
	v_lshl_add_u64 v[54:55], v[28:29], 0, s[58:59]
	ds_read2_b64 v[40:43], v36 offset0:64 offset1:96
	v_cmp_le_i64_e32 vcc, s[50:51], v[54:55]
	v_cmp_gt_i64_e64 s[42:43], s[52:53], v[54:55]
	s_and_b64 s[62:63], vcc, s[42:43]
	v_cmp_lt_i32_e32 vcc, 0, v52
	v_cmp_eq_u64_e64 s[42:43], s[58:59], v[10:11]
	s_or_b64 s[42:43], vcc, s[42:43]
	s_and_b64 s[62:63], s[62:63], s[42:43]
	v_cmp_gt_i32_e32 vcc, s27, v52
	v_cmp_eq_u64_e64 s[42:43], s[58:59], v[32:33]
	s_or_b64 s[42:43], vcc, s[42:43]
	s_waitcnt lgkmcnt(0)
	v_lshlrev_b32_e32 v36, 16, v40
	v_lshlrev_b32_e32 v37, 16, v41
	v_and_b32_e32 v39, 0xffff0000, v41
	v_and_b32_e32 v38, 0xffff0000, v40
	v_lshlrev_b32_e32 v40, 16, v42
	v_lshlrev_b32_e32 v41, 16, v43
	v_and_b32_e32 v43, 0xffff0000, v43
	v_and_b32_e32 v42, 0xffff0000, v42
	s_and_b64 s[62:63], s[62:63], s[42:43]
	s_and_saveexec_b64 s[42:43], s[62:63]
	s_cbranch_execz .LBB0_1114
	v_cmp_lt_i64_e32 vcc, s[50:51], v[54:55]
	v_pk_mul_f32 v[58:59], v[12:13], v[58:59]
	v_pk_mul_f32 v[56:57], v[22:23], v[56:57]
	v_cndmask_b32_e64 v66, 0, 1.0, vcc
	v_cmp_gt_i64_e32 vcc, s[56:57], v[54:55]
	v_pk_mul_f32 v[58:59], v[58:59], v[66:67] op_sel_hi:[1,0]
	v_pk_mul_f32 v[70:71], v[14:15], v[36:37]
	v_cndmask_b32_e64 v68, 0, 1.0, vcc
	v_pk_fma_f32 v[58:59], v[0:1], v[46:47], v[58:59]
	v_pk_mul_f32 v[56:57], v[56:57], v[66:67] op_sel_hi:[1,0]
	v_pk_mul_f32 v[74:75], v[20:21], v[38:39]
	v_pk_fma_f32 v[58:59], v[70:71], v[68:69], v[58:59] op_sel_hi:[1,0,1]
	v_pk_fma_f32 v[56:57], v[8:9], v[44:45], v[56:57]
	v_mul_f32_e32 v53, 0xbfb8aa3b, v58
	v_pk_fma_f32 v[56:57], v[74:75], v[68:69], v[56:57] op_sel_hi:[1,0,1]
	v_exp_f32_e32 v70, v53
	v_mul_f32_e32 v53, 0xbfb8aa3b, v56
	v_exp_f32_e32 v74, v53
	v_mul_f32_e32 v53, 0xbfb8aa3b, v59
	v_exp_f32_e32 v71, v53
	v_pk_mul_f32 v[62:63], v[4:5], v[62:63]
	v_pk_mul_f32 v[72:73], v[6:7], v[40:41]
	v_pk_mul_f32 v[62:63], v[62:63], v[66:67] op_sel_hi:[1,0]
	v_pk_add_f32 v[70:71], v[70:71], 1.0 op_sel_hi:[1,0]
	v_pk_fma_f32 v[62:63], v[24:25], v[50:51], v[62:63]
	v_pk_fma_f32 v[62:63], v[68:69], v[72:73], v[62:63] op_sel_hi:[0,1,1]
	v_pk_mul_f32 v[60:61], v[18:19], v[60:61]
	v_pk_mul_f32 v[76:77], v[2:3], v[42:43]
	s_nop 0
	v_div_scale_f32 v80, vcc, v70, v70, v58
	v_div_scale_f32 v81, vcc, v71, v71, v59
	v_rcp_f32_e32 v82, v80
	v_rcp_f32_e32 v83, v81
	v_div_scale_f32 v86, s[62:63], v58, v70, v58
	v_div_scale_f32 v87, vcc, v59, v71, v59
	v_pk_fma_f32 v[84:85], v[80:81], v[82:83], 1.0 op_sel_hi:[1,1,0] neg_lo:[1,0,0] neg_hi:[1,0,0]
	v_pk_fma_f32 v[82:83], v[84:85], v[82:83], v[82:83]
	v_pk_mul_f32 v[88:89], v[86:87], v[82:83]
	v_pk_fma_f32 v[84:85], v[80:81], v[88:89], v[86:87] neg_lo:[1,0,0] neg_hi:[1,0,0]
	v_pk_fma_f32 v[88:89], v[84:85], v[82:83], v[88:89]
	v_pk_fma_f32 v[84:85], v[80:81], v[88:89], v[86:87] neg_lo:[1,0,0] neg_hi:[1,0,0]
	v_div_fmas_f32 v85, v85, v83, v89
	s_mov_b64 vcc, s[62:63]
	s_nop 0
	v_div_fmas_f32 v84, v84, v82, v88
	v_div_fixup_f32 v59, v85, v71, v59
	v_div_fixup_f32 v58, v84, v70, v58
	v_mul_f32_e32 v53, 0xbfb8aa3b, v57
	v_exp_f32_e32 v75, v53
	v_pk_mul_f32 v[58:59], v[62:63], v[58:59]
	v_pk_mul_f32 v[60:61], v[60:61], v[66:67] op_sel_hi:[1,0]
	v_pk_add_f32 v[62:63], v[74:75], 1.0 op_sel_hi:[1,0]
	s_nop 0
	v_pk_fma_f32 v[60:61], v[16:17], v[48:49], v[60:61]
	v_pk_fma_f32 v[60:61], v[68:69], v[76:77], v[60:61] op_sel_hi:[0,1,1]
	s_nop 0
	v_div_scale_f32 v80, vcc, v62, v62, v56
	v_div_scale_f32 v81, vcc, v63, v63, v57
	v_rcp_f32_e32 v82, v80
	v_rcp_f32_e32 v83, v81
	v_div_scale_f32 v86, s[62:63], v56, v62, v56
	v_div_scale_f32 v87, vcc, v57, v63, v57
	v_pk_fma_f32 v[84:85], v[80:81], v[82:83], 1.0 op_sel_hi:[1,1,0] neg_lo:[1,0,0] neg_hi:[1,0,0]
	v_pk_fma_f32 v[82:83], v[84:85], v[82:83], v[82:83]
	v_pk_mul_f32 v[88:89], v[86:87], v[82:83]
	v_pk_fma_f32 v[84:85], v[80:81], v[88:89], v[86:87] neg_lo:[1,0,0] neg_hi:[1,0,0]
	v_pk_fma_f32 v[88:89], v[84:85], v[82:83], v[88:89]
	v_pk_fma_f32 v[84:85], v[80:81], v[88:89], v[86:87] neg_lo:[1,0,0] neg_hi:[1,0,0]
	v_div_fmas_f32 v85, v85, v83, v89
	s_mov_b64 vcc, s[62:63]
	s_nop 0
	v_div_fmas_f32 v84, v84, v82, v88
	v_div_fixup_f32 v57, v85, v63, v57
	v_div_fixup_f32 v56, v84, v62, v56
	v_pk_mul_f32 v[56:57], v[60:61], v[56:57]
	v_cvt_pk_bf16_f32 v56, v58, v56
	v_cvt_pk_bf16_f32 v57, v59, v57
	v_add_co_u32_e32 v58, vcc, 0xffffe000, v30
	s_nop 1
	v_addc_co_u32_e32 v59, vcc, -1, v31, vcc
	global_store_dwordx2 v[58:59], v[56:57], off offset:-3072

; #define STAGE(P, BASE, br, kt) STAGET(tid_, P, BASE, br, kt)
; #define LDA(dst, b, h) UFOR(m, 4) UFOR(k, 2) \
;     dst[m][k] = *reinterpret_cast<const bf16x8*>((char*)SA(b, h) + lds_byte(wr * 64 + m * 16 + fr, k * 32 + fq * 8))
; #define LDB(dst, b, h) UFOR(n, 2) UFOR(k, 2) \
;     dst[n][k] = *reinterpret_cast<const bf16x8*>((char*)SB(b, h) + lds_byte(wc * 32 + n * 16 + fr, k * 32 + fq * 8))
; #define WAIT_V(n) asm volatile("s_waitcnt vmcnt(" #n ")" ::: "memory")
; #define WAIT_L(n) asm volatile("s_waitcnt lgkmcnt(" #n ")" ::: "memory")
; #define BAR __builtin_amdgcn_s_barrier()
; template <int EPI, int K, int KL> ...
;     ...
;   for (int t = 0; t < nt - 2; t += 2) {
;     LDB(B0, 0, 0); SCHED; LDA(At, 0, 0); STAGE(SA(1, 1), A, brow + HALF, t + 1);
;     WAIT_L(8); BAR; WAIT_L(0); MMA(0, 0, At, B0); BAR; SCHED;
;     LDB(B1, 0, 1); STAGE(SB(0, 0), Bt, bcol, t + 2);
;     BAR; WAIT_L(0); MMA(0, 1, At, B1); BAR;
;     LDA(At, 0, 1); STAGE(SA(0, 0), A, brow, t + 2);
;     BAR; WAIT_L(0); MMA(1, 0, At, B0); BAR; SCHED;
;     STAGE(SB(0, 1), Bt, bcol + HALF, t + 2);
;     WAIT_V(6); BAR; MMA(1, 1, At, B1); BAR;
;     LDB(B0, 1, 0); SCHED; LDA(At, 1, 0); STAGE(SA(0, 1), A, brow + HALF, t + 2);
;     WAIT_L(8); BAR; WAIT_L(0); MMA(0, 0, At, B0); BAR; SCHED;
;     LDB(B1, 1, 1); STAGE(SB(1, 0), Bt, bcol, t + 3);
;     BAR; WAIT_L(0); MMA(0, 1, At, B1); BAR;
;     LDA(At, 1, 1); STAGE(SA(1, 0), A, brow, t + 3);
;     BAR; WAIT_L(0); MMA(1, 0, At, B0); BAR; SCHED;
;     STAGE(SB(1, 1), Bt, bcol + HALF, t + 3);
;     WAIT_V(6); BAR; MMA(1, 1, At, B1); BAR;
;   }
;   { LDB(B0, 0, 0); LDA(At, 0, 0); STAGE(SA(1, 1), A, brow + HALF, nt - 1);
;     BAR; WAIT_L(0); MMA(0, 0, At, B0); BAR;
;     LDB(B1, 0, 1); BAR; WAIT_L(0); MMA(0, 1, At, B1); BAR;
;     LDA(At, 0, 1); WAIT_V(4); BAR; WAIT_L(0); MMA(1, 0, At, B0); MMA(1, 1, At, B1); BAR; }
; __device__ __forceinline__ void gemm_ctx_splitk_down(const u16* A, const u16* Bt, float* P2, const EpiArgs& e0) {
;     ...
;   for (int u = bid_; u < 16 * P2_PARTS; u += gridDim.x) {
;     const int tile = u / P2_PARTS, part = u % P2_PARTS, pm = 128 + (tile >> 3), pn = tile & 7;
;     EpiArgs e = e0; e.part = P2 + (size_t)part * 512 * DM;
;     const long koff = (long)part * (DFF / P2_PARTS);
;     gemm_tile<EPI_PART, DFF, DFF / P2_PARTS>(A + koff, Bt + koff, (long)pm * BM, pn * BM, pn, 0, 0, e, true, false, 0, 0);
.LBB0_1204:
	ds_read_b128 v[136:139], v175
	ds_read_b128 v[178:181], v175 offset:1024
	ds_read_b128 v[182:185], v175 offset:2048
	ds_read_b128 v[186:189], v175 offset:3072
	v_add_u32_e32 v176, 0xc000, v161
	v_lshl_add_u64 v[152:153], v[148:149], 0, s[44:45]
	v_readfirstlane_b32 s15, v176
	v_lshl_add_u64 v[154:155], v[152:153], 0, s[58:59]
	s_mov_b32 m0, s15
	v_add_u32_e32 v177, 0xe000, v161
	ds_read_b128 v[190:193], v160
	ds_read_b128 v[194:197], v160 offset:1024
	ds_read_b128 v[198:201], v159
	ds_read_b128 v[202:205], v159 offset:1024
	ds_read_b128 v[208:211], v158
	ds_read_b128 v[214:217], v158 offset:1024
	ds_read_b128 v[218:221], v157
	ds_read_b128 v[222:225], v157 offset:1024
	global_load_lds_dwordx4 v[154:155], off
	v_lshl_add_u64 v[154:155], v[150:151], 0, s[44:45]
	v_readfirstlane_b32 s15, v177
	v_lshl_add_u64 v[226:227], v[154:155], 0, s[58:59]
	s_mov_b32 m0, s15
	s_nop 0
	global_load_lds_dwordx4 v[226:227], off
	s_waitcnt lgkmcnt(8)
	s_barrier
	s_waitcnt lgkmcnt(0)
	s_waitcnt lgkmcnt(0)
	v_mfma_f32_16x16x32_bf16 v[124:127], v[136:139], v[190:193], v[124:127]
	v_mfma_f32_16x16x32_bf16 v[120:123], v[182:185], v[190:193], v[120:123]
	v_mfma_f32_16x16x32_bf16 v[116:119], v[136:139], v[198:201], v[116:119]
	v_mfma_f32_16x16x32_bf16 v[112:115], v[182:185], v[198:201], v[112:115]
	v_mfma_f32_16x16x32_bf16 v[108:111], v[136:139], v[208:211], v[108:111]
	v_mfma_f32_16x16x32_bf16 v[104:107], v[182:185], v[208:211], v[104:107]
	v_mfma_f32_16x16x32_bf16 v[100:103], v[136:139], v[218:221], v[100:103]
	v_mfma_f32_16x16x32_bf16 v[96:99], v[182:185], v[218:221], v[96:99]
	v_mfma_f32_16x16x32_bf16 v[124:127], v[178:181], v[194:197], v[124:127]
	v_mfma_f32_16x16x32_bf16 v[120:123], v[186:189], v[194:197], v[120:123]
	v_mfma_f32_16x16x32_bf16 v[116:119], v[178:181], v[202:205], v[116:119]
	v_mfma_f32_16x16x32_bf16 v[112:115], v[186:189], v[202:205], v[112:115]
	v_mfma_f32_16x16x32_bf16 v[108:111], v[178:181], v[214:217], v[108:111]
	v_mfma_f32_16x16x32_bf16 v[104:107], v[186:189], v[214:217], v[104:107]
	v_mfma_f32_16x16x32_bf16 v[100:103], v[178:181], v[222:225], v[100:103]
	v_mfma_f32_16x16x32_bf16 v[96:99], v[186:189], v[222:225], v[96:99]
	s_barrier
	v_lshl_add_u64 v[242:243], v[144:145], 0, s[44:45]
	v_readfirstlane_b32 s15, v156
	v_lshl_add_u64 v[244:245], v[242:243], 0, s[22:23]
	s_mov_b32 m0, s15
	v_add_u32_e32 v248, 0x2000, v156
	ds_read_b128 v[226:229], v173
	ds_read_b128 v[230:233], v173 offset:1024
	ds_read_b128 v[234:237], v173 offset:2048
	ds_read_b128 v[238:241], v173 offset:3072
	global_load_lds_dwordx4 v[244:245], off
	v_lshl_add_u64 v[244:245], v[146:147], 0, s[44:45]
	v_readfirstlane_b32 s15, v248
	v_lshl_add_u64 v[246:247], v[244:245], 0, s[22:23]
	s_mov_b32 m0, s15
	s_nop 0
	global_load_lds_dwordx4 v[246:247], off
	s_barrier
	s_waitcnt lgkmcnt(0)
	s_waitcnt lgkmcnt(0)
	v_mfma_f32_16x16x32_bf16 v[92:95], v[226:229], v[190:193], v[92:95]
	v_mfma_f32_16x16x32_bf16 v[88:91], v[234:237], v[190:193], v[88:91]
	v_mfma_f32_16x16x32_bf16 v[84:87], v[226:229], v[198:201], v[84:87]
	v_mfma_f32_16x16x32_bf16 v[80:83], v[234:237], v[198:201], v[80:83]
	v_mfma_f32_16x16x32_bf16 v[76:79], v[226:229], v[208:211], v[76:79]
	v_mfma_f32_16x16x32_bf16 v[72:75], v[234:237], v[208:211], v[72:75]
	v_mfma_f32_16x16x32_bf16 v[68:71], v[226:229], v[218:221], v[68:71]
	v_mfma_f32_16x16x32_bf16 v[64:67], v[234:237], v[218:221], v[64:67]
	v_mfma_f32_16x16x32_bf16 v[92:95], v[230:233], v[194:197], v[92:95]
	v_mfma_f32_16x16x32_bf16 v[88:91], v[238:241], v[194:197], v[88:91]
	v_mfma_f32_16x16x32_bf16 v[84:87], v[230:233], v[202:205], v[84:87]
	v_mfma_f32_16x16x32_bf16 v[80:83], v[238:241], v[202:205], v[80:83]
	v_mfma_f32_16x16x32_bf16 v[76:79], v[230:233], v[214:217], v[76:79]
	v_mfma_f32_16x16x32_bf16 v[72:75], v[238:241], v[214:217], v[72:75]
	v_mfma_f32_16x16x32_bf16 v[68:71], v[230:233], v[222:225], v[68:71]
	v_mfma_f32_16x16x32_bf16 v[64:67], v[238:241], v[222:225], v[64:67]
	v_readfirstlane_b32 s15, v161
	v_lshl_add_u64 v[246:247], v[152:153], 0, s[60:61]
	s_mov_b32 m0, s15
	v_readfirstlane_b32 s15, v162
	s_barrier
	ds_read_b128 v[190:193], v160 offset:16384
	ds_read_b128 v[194:197], v160 offset:17408
	ds_read_b128 v[198:201], v159 offset:16384
	ds_read_b128 v[202:205], v159 offset:17408
	ds_read_b128 v[208:211], v158 offset:16384
	ds_read_b128 v[214:217], v158 offset:17408
	ds_read_b128 v[218:221], v157 offset:16384
	ds_read_b128 v[222:225], v157 offset:17408
	global_load_lds_dwordx4 v[246:247], off
	v_lshl_add_u64 v[246:247], v[154:155], 0, s[60:61]
	s_mov_b32 m0, s15
	s_nop 0
	global_load_lds_dwordx4 v[246:247], off
	s_barrier
	s_waitcnt lgkmcnt(0)
	s_waitcnt lgkmcnt(0)
	v_mfma_f32_16x16x32_bf16 v[60:63], v[136:139], v[190:193], v[60:63]
	v_mfma_f32_16x16x32_bf16 v[56:59], v[182:185], v[190:193], v[56:59]
	v_mfma_f32_16x16x32_bf16 v[52:55], v[136:139], v[198:201], v[52:55]
	v_mfma_f32_16x16x32_bf16 v[48:51], v[182:185], v[198:201], v[48:51]
	v_mfma_f32_16x16x32_bf16 v[44:47], v[136:139], v[208:211], v[44:47]
	v_mfma_f32_16x16x32_bf16 v[40:43], v[182:185], v[208:211], v[40:43]
	v_mfma_f32_16x16x32_bf16 v[36:39], v[136:139], v[218:221], v[36:39]
	v_mfma_f32_16x16x32_bf16 v[32:35], v[182:185], v[218:221], v[32:35]
	v_mfma_f32_16x16x32_bf16 v[60:63], v[178:181], v[194:197], v[60:63]
	v_mfma_f32_16x16x32_bf16 v[56:59], v[186:189], v[194:197], v[56:59]
	v_mfma_f32_16x16x32_bf16 v[52:55], v[178:181], v[202:205], v[52:55]
	v_mfma_f32_16x16x32_bf16 v[48:51], v[186:189], v[202:205], v[48:51]
	v_mfma_f32_16x16x32_bf16 v[44:47], v[178:181], v[214:217], v[44:47]
	v_mfma_f32_16x16x32_bf16 v[40:43], v[186:189], v[214:217], v[40:43]
	v_mfma_f32_16x16x32_bf16 v[36:39], v[178:181], v[222:225], v[36:39]
	v_mfma_f32_16x16x32_bf16 v[32:35], v[186:189], v[222:225], v[32:35]
	s_barrier
; #define STAGE(P, BASE, br, kt) STAGET(tid_, P, BASE, br, kt)
; #define LDA(dst, b, h) UFOR(m, 4) UFOR(k, 2) \
;     dst[m][k] = *reinterpret_cast<const bf16x8*>((char*)SA(b, h) + lds_byte(wr * 64 + m * 16 + fr, k * 32 + fq * 8))
; #define LDB(dst, b, h) UFOR(n, 2) UFOR(k, 2) \
;     dst[n][k] = *reinterpret_cast<const bf16x8*>((char*)SB(b, h) + lds_byte(wc * 32 + n * 16 + fr, k * 32 + fq * 8))
; #define MMA(ai, bj, At, Bq) do { __builtin_amdgcn_s_setprio(1); \
;     UFOR(m, 4) UFOR(n, 2) UFOR(k, 2) \
;       acc[ai][bj][m][n] = __builtin_amdgcn_mfma_f32_16x16x32_bf16(Bq[n][k], At[m][k], acc[ai][bj][m][n], 0, 0, 0); \
;     __builtin_amdgcn_s_setprio(0); } while (0)
; #define WAIT_V(n) asm volatile("s_waitcnt vmcnt(" #n ")" ::: "memory")
; #define WAIT_L(n) asm volatile("s_waitcnt lgkmcnt(" #n ")" ::: "memory")
; #define BAR __builtin_amdgcn_s_barrier()
; #define SCHED __builtin_amdgcn_sched_barrier(0)
; template <int EPI, int K, int KL> ...
;     ...
;   for (int t = 0; t < nt - 2; t += 2) {
;     LDB(B0, 0, 0); SCHED; LDA(At, 0, 0); STAGE(SA(1, 1), A, brow + HALF, t + 1);
;     WAIT_L(8); BAR; WAIT_L(0); MMA(0, 0, At, B0); BAR; SCHED;
;     LDB(B1, 0, 1); STAGE(SB(0, 0), Bt, bcol, t + 2);
;     BAR; WAIT_L(0); MMA(0, 1, At, B1); BAR;
;     LDA(At, 0, 1); STAGE(SA(0, 0), A, brow, t + 2);
;     BAR; WAIT_L(0); MMA(1, 0, At, B0); BAR; SCHED;
;     STAGE(SB(0, 1), Bt, bcol + HALF, t + 2);
;     WAIT_V(6); BAR; MMA(1, 1, At, B1); BAR;
;     LDB(B0, 1, 0); SCHED; LDA(At, 1, 0); STAGE(SA(0, 1), A, brow + HALF, t + 2);
;     WAIT_L(8); BAR; WAIT_L(0); MMA(0, 0, At, B0); BAR; SCHED;
;     LDB(B1, 1, 1); STAGE(SB(1, 0), Bt, bcol, t + 3);
;     BAR; WAIT_L(0); MMA(0, 1, At, B1); BAR;
;     LDA(At, 1, 1); STAGE(SA(1, 0), A, brow, t + 3);
;     BAR; WAIT_L(0); MMA(1, 0, At, B0); BAR; SCHED;
;     STAGE(SB(1, 1), Bt, bcol + HALF, t + 3);
;     WAIT_V(6); BAR; MMA(1, 1, At, B1); BAR;
;   }
;   { LDB(B0, 0, 0); LDA(At, 0, 0); STAGE(SA(1, 1), A, brow + HALF, nt - 1);
;     BAR; WAIT_L(0); MMA(0, 0, At, B0); BAR;
;     LDB(B1, 0, 1); BAR; WAIT_L(0); MMA(0, 1, At, B1); BAR;
;     LDA(At, 0, 1); WAIT_V(4); BAR; WAIT_L(0); MMA(1, 0, At, B0); MMA(1, 1, At, B1); BAR; }
	v_readfirstlane_b32 s15, v164
	v_add_u32_e32 v138, 0x2000, v164
	v_lshl_add_u64 v[136:137], v[242:243], 0, s[24:25]
	s_mov_b32 m0, s15
	v_readfirstlane_b32 s15, v138
	global_load_lds_dwordx4 v[136:137], off
	v_lshl_add_u64 v[136:137], v[244:245], 0, s[24:25]
	s_mov_b32 m0, s15
	s_nop 0
	global_load_lds_dwordx4 v[136:137], off
	s_waitcnt vmcnt(6)
	s_barrier
	v_mfma_f32_16x16x32_bf16 v[28:31], v[226:229], v[190:193], v[28:31]
	v_mfma_f32_16x16x32_bf16 v[24:27], v[234:237], v[190:193], v[24:27]
	v_mfma_f32_16x16x32_bf16 v[20:23], v[226:229], v[198:201], v[20:23]
	v_mfma_f32_16x16x32_bf16 v[16:19], v[234:237], v[198:201], v[16:19]
	v_mfma_f32_16x16x32_bf16 v[12:15], v[226:229], v[208:211], v[12:15]
	v_mfma_f32_16x16x32_bf16 v[8:11], v[234:237], v[208:211], v[8:11]
	v_mfma_f32_16x16x32_bf16 v[4:7], v[226:229], v[218:221], v[4:7]
	v_mfma_f32_16x16x32_bf16 v[0:3], v[234:237], v[218:221], v[0:3]
	v_mfma_f32_16x16x32_bf16 v[28:31], v[230:233], v[194:197], v[28:31]
	v_mfma_f32_16x16x32_bf16 v[24:27], v[238:241], v[194:197], v[24:27]
	v_mfma_f32_16x16x32_bf16 v[20:23], v[230:233], v[202:205], v[20:23]
	v_mfma_f32_16x16x32_bf16 v[16:19], v[238:241], v[202:205], v[16:19]
	v_mfma_f32_16x16x32_bf16 v[12:15], v[230:233], v[214:217], v[12:15]
	v_mfma_f32_16x16x32_bf16 v[8:11], v[238:241], v[214:217], v[8:11]
	v_mfma_f32_16x16x32_bf16 v[4:7], v[230:233], v[222:225], v[4:7]
	v_mfma_f32_16x16x32_bf16 v[0:3], v[238:241], v[222:225], v[0:3]
	s_barrier
	ds_read_b128 v[136:139], v166
	ds_read_b128 v[178:181], v166 offset:1024
	ds_read_b128 v[182:185], v166 offset:2048
	ds_read_b128 v[186:189], v166 offset:3072
	v_readfirstlane_b32 s15, v165
	v_lshl_add_u64 v[226:227], v[152:153], 0, s[62:63]
	s_mov_b32 m0, s15
	v_readfirstlane_b32 s15, v167
	ds_read_b128 v[190:193], v160 offset:32768
	ds_read_b128 v[194:197], v160 offset:33792
	ds_read_b128 v[198:201], v159 offset:32768
	ds_read_b128 v[202:205], v159 offset:33792
	ds_read_b128 v[208:211], v158 offset:32768
	ds_read_b128 v[214:217], v158 offset:33792
	ds_read_b128 v[218:221], v157 offset:32768
	ds_read_b128 v[222:225], v157 offset:33792
	global_load_lds_dwordx4 v[226:227], off
	v_lshl_add_u64 v[226:227], v[154:155], 0, s[62:63]
	s_mov_b32 m0, s15
	s_nop 0
	global_load_lds_dwordx4 v[226:227], off
	s_waitcnt lgkmcnt(8)
	s_barrier
	s_waitcnt lgkmcnt(0)
	s_waitcnt lgkmcnt(0)
	v_mfma_f32_16x16x32_bf16 v[124:127], v[136:139], v[190:193], v[124:127]
	v_mfma_f32_16x16x32_bf16 v[120:123], v[182:185], v[190:193], v[120:123]
	v_mfma_f32_16x16x32_bf16 v[116:119], v[136:139], v[198:201], v[116:119]
	v_mfma_f32_16x16x32_bf16 v[112:115], v[182:185], v[198:201], v[112:115]
	v_mfma_f32_16x16x32_bf16 v[108:111], v[136:139], v[208:211], v[108:111]
	v_mfma_f32_16x16x32_bf16 v[104:107], v[182:185], v[208:211], v[104:107]
	v_mfma_f32_16x16x32_bf16 v[100:103], v[136:139], v[218:221], v[100:103]
	v_mfma_f32_16x16x32_bf16 v[96:99], v[182:185], v[218:221], v[96:99]
	v_mfma_f32_16x16x32_bf16 v[124:127], v[178:181], v[194:197], v[124:127]
	v_mfma_f32_16x16x32_bf16 v[120:123], v[186:189], v[194:197], v[120:123]
	v_mfma_f32_16x16x32_bf16 v[116:119], v[178:181], v[202:205], v[116:119]
	v_mfma_f32_16x16x32_bf16 v[112:115], v[186:189], v[202:205], v[112:115]
	v_mfma_f32_16x16x32_bf16 v[108:111], v[178:181], v[214:217], v[108:111]
	v_mfma_f32_16x16x32_bf16 v[104:107], v[186:189], v[214:217], v[104:107]
	v_mfma_f32_16x16x32_bf16 v[100:103], v[178:181], v[222:225], v[100:103]
	v_mfma_f32_16x16x32_bf16 v[96:99], v[186:189], v[222:225], v[96:99]
	s_barrier
	v_readfirstlane_b32 s15, v168
	v_lshl_add_u64 v[246:247], v[242:243], 0, s[94:95]
	s_mov_b32 m0, s15
	v_readfirstlane_b32 s15, v169
	ds_read_b128 v[226:229], v163
	ds_read_b128 v[230:233], v163 offset:1024
	ds_read_b128 v[234:237], v163 offset:2048
	ds_read_b128 v[238:241], v163 offset:3072
	global_load_lds_dwordx4 v[246:247], off
	v_lshl_add_u64 v[246:247], v[244:245], 0, s[94:95]
	s_mov_b32 m0, s15
	s_nop 0
	global_load_lds_dwordx4 v[246:247], off
	s_barrier
	s_waitcnt lgkmcnt(0)
	s_waitcnt lgkmcnt(0)
	v_mfma_f32_16x16x32_bf16 v[92:95], v[226:229], v[190:193], v[92:95]
	v_mfma_f32_16x16x32_bf16 v[88:91], v[234:237], v[190:193], v[88:91]
	v_mfma_f32_16x16x32_bf16 v[84:87], v[226:229], v[198:201], v[84:87]
	v_mfma_f32_16x16x32_bf16 v[80:83], v[234:237], v[198:201], v[80:83]
	v_mfma_f32_16x16x32_bf16 v[76:79], v[226:229], v[208:211], v[76:79]
	v_mfma_f32_16x16x32_bf16 v[72:75], v[234:237], v[208:211], v[72:75]
	v_mfma_f32_16x16x32_bf16 v[68:71], v[226:229], v[218:221], v[68:71]
	v_mfma_f32_16x16x32_bf16 v[64:67], v[234:237], v[218:221], v[64:67]
	v_mfma_f32_16x16x32_bf16 v[92:95], v[230:233], v[194:197], v[92:95]
	v_mfma_f32_16x16x32_bf16 v[88:91], v[238:241], v[194:197], v[88:91]
	v_mfma_f32_16x16x32_bf16 v[84:87], v[230:233], v[202:205], v[84:87]
	v_mfma_f32_16x16x32_bf16 v[80:83], v[238:241], v[202:205], v[80:83]
	v_mfma_f32_16x16x32_bf16 v[76:79], v[230:233], v[214:217], v[76:79]
	v_mfma_f32_16x16x32_bf16 v[72:75], v[238:241], v[214:217], v[72:75]
	v_mfma_f32_16x16x32_bf16 v[68:71], v[230:233], v[222:225], v[68:71]
	v_mfma_f32_16x16x32_bf16 v[64:67], v[238:241], v[222:225], v[64:67]
	v_readfirstlane_b32 s15, v170
	v_lshl_add_u64 v[152:153], v[152:153], 0, s[64:65]
	s_mov_b32 m0, s15
	v_readfirstlane_b32 s15, v171
	s_barrier
	ds_read_b128 v[190:193], v160 offset:49152
	ds_read_b128 v[194:197], v160 offset:50176
	ds_read_b128 v[198:201], v159 offset:49152
	ds_read_b128 v[202:205], v159 offset:50176
	ds_read_b128 v[208:211], v158 offset:49152
	ds_read_b128 v[214:217], v158 offset:50176
	ds_read_b128 v[218:221], v157 offset:49152
	ds_read_b128 v[222:225], v157 offset:50176
	global_load_lds_dwordx4 v[152:153], off
	v_lshl_add_u64 v[152:153], v[154:155], 0, s[64:65]
	s_mov_b32 m0, s15
	s_nop 0
	global_load_lds_dwordx4 v[152:153], off
	s_barrier
; #define STAGE(P, BASE, br, kt) STAGET(tid_, P, BASE, br, kt)
; #define LDA(dst, b, h) UFOR(m, 4) UFOR(k, 2) \
;     dst[m][k] = *reinterpret_cast<const bf16x8*>((char*)SA(b, h) + lds_byte(wr * 64 + m * 16 + fr, k * 32 + fq * 8))
; #define LDB(dst, b, h) UFOR(n, 2) UFOR(k, 2) \
;     dst[n][k] = *reinterpret_cast<const bf16x8*>((char*)SB(b, h) + lds_byte(wc * 32 + n * 16 + fr, k * 32 + fq * 8))
; #define MMA(ai, bj, At, Bq) do { __builtin_amdgcn_s_setprio(1); \
;     UFOR(m, 4) UFOR(n, 2) UFOR(k, 2) \
;       acc[ai][bj][m][n] = __builtin_amdgcn_mfma_f32_16x16x32_bf16(Bq[n][k], At[m][k], acc[ai][bj][m][n], 0, 0, 0); \
;     __builtin_amdgcn_s_setprio(0); } while (0)
; #define WAIT_V(n) asm volatile("s_waitcnt vmcnt(" #n ")" ::: "memory")
; #define WAIT_L(n) asm volatile("s_waitcnt lgkmcnt(" #n ")" ::: "memory")
; #define BAR __builtin_amdgcn_s_barrier()
; #define SCHED __builtin_amdgcn_sched_barrier(0)
; template <int EPI, int K, int KL> ...
;     ...
;   for (int t = 0; t < nt - 2; t += 2) {
;     LDB(B0, 0, 0); SCHED; LDA(At, 0, 0); STAGE(SA(1, 1), A, brow + HALF, t + 1);
;     WAIT_L(8); BAR; WAIT_L(0); MMA(0, 0, At, B0); BAR; SCHED;
;     LDB(B1, 0, 1); STAGE(SB(0, 0), Bt, bcol, t + 2);
;     BAR; WAIT_L(0); MMA(0, 1, At, B1); BAR;
;     LDA(At, 0, 1); STAGE(SA(0, 0), A, brow, t + 2);
;     BAR; WAIT_L(0); MMA(1, 0, At, B0); BAR; SCHED;
;     STAGE(SB(0, 1), Bt, bcol + HALF, t + 2);
;     WAIT_V(6); BAR; MMA(1, 1, At, B1); BAR;
;     LDB(B0, 1, 0); SCHED; LDA(At, 1, 0); STAGE(SA(0, 1), A, brow + HALF, t + 2);
;     WAIT_L(8); BAR; WAIT_L(0); MMA(0, 0, At, B0); BAR; SCHED;
;     LDB(B1, 1, 1); STAGE(SB(1, 0), Bt, bcol, t + 3);
;     BAR; WAIT_L(0); MMA(0, 1, At, B1); BAR;
;     LDA(At, 1, 1); STAGE(SA(1, 0), A, brow, t + 3);
;     BAR; WAIT_L(0); MMA(1, 0, At, B0); BAR; SCHED;
;     STAGE(SB(1, 1), Bt, bcol + HALF, t + 3);
;     WAIT_V(6); BAR; MMA(1, 1, At, B1); BAR;
;   }
;   { LDB(B0, 0, 0); LDA(At, 0, 0); STAGE(SA(1, 1), A, brow + HALF, nt - 1);
;     BAR; WAIT_L(0); MMA(0, 0, At, B0); BAR;
;     LDB(B1, 0, 1); BAR; WAIT_L(0); MMA(0, 1, At, B1); BAR;
;     LDA(At, 0, 1); WAIT_V(4); BAR; WAIT_L(0); MMA(1, 0, At, B0); MMA(1, 1, At, B1); BAR; }
	s_waitcnt lgkmcnt(0)
	s_waitcnt lgkmcnt(0)
	v_mfma_f32_16x16x32_bf16 v[60:63], v[136:139], v[190:193], v[60:63]
	v_mfma_f32_16x16x32_bf16 v[56:59], v[182:185], v[190:193], v[56:59]
	v_mfma_f32_16x16x32_bf16 v[52:55], v[136:139], v[198:201], v[52:55]
	v_mfma_f32_16x16x32_bf16 v[48:51], v[182:185], v[198:201], v[48:51]
	v_mfma_f32_16x16x32_bf16 v[44:47], v[136:139], v[208:211], v[44:47]
	v_mfma_f32_16x16x32_bf16 v[40:43], v[182:185], v[208:211], v[40:43]
	v_mfma_f32_16x16x32_bf16 v[36:39], v[136:139], v[218:221], v[36:39]
	v_mfma_f32_16x16x32_bf16 v[32:35], v[182:185], v[218:221], v[32:35]
	v_mfma_f32_16x16x32_bf16 v[60:63], v[178:181], v[194:197], v[60:63]
	v_mfma_f32_16x16x32_bf16 v[56:59], v[186:189], v[194:197], v[56:59]
	v_mfma_f32_16x16x32_bf16 v[52:55], v[178:181], v[202:205], v[52:55]
	v_mfma_f32_16x16x32_bf16 v[48:51], v[186:189], v[202:205], v[48:51]
	v_mfma_f32_16x16x32_bf16 v[44:47], v[178:181], v[214:217], v[44:47]
	v_mfma_f32_16x16x32_bf16 v[40:43], v[186:189], v[214:217], v[40:43]
	v_mfma_f32_16x16x32_bf16 v[36:39], v[178:181], v[222:225], v[36:39]
	v_mfma_f32_16x16x32_bf16 v[32:35], v[186:189], v[222:225], v[32:35]
	s_barrier
	v_readfirstlane_b32 s15, v172
	v_lshl_add_u64 v[136:137], v[242:243], 0, s[10:11]
	s_mov_b32 m0, s15
	v_readfirstlane_b32 s15, v174
	global_load_lds_dwordx4 v[136:137], off
	v_lshl_add_u64 v[136:137], v[244:245], 0, s[10:11]
	s_mov_b32 m0, s15
	s_nop 0
	global_load_lds_dwordx4 v[136:137], off
	s_waitcnt vmcnt(6)
	s_barrier
	v_mfma_f32_16x16x32_bf16 v[28:31], v[226:229], v[190:193], v[28:31]
	v_mfma_f32_16x16x32_bf16 v[24:27], v[234:237], v[190:193], v[24:27]
	v_mfma_f32_16x16x32_bf16 v[20:23], v[226:229], v[198:201], v[20:23]
	v_mfma_f32_16x16x32_bf16 v[16:19], v[234:237], v[198:201], v[16:19]
	v_mfma_f32_16x16x32_bf16 v[12:15], v[226:229], v[208:211], v[12:15]
	v_mfma_f32_16x16x32_bf16 v[8:11], v[234:237], v[208:211], v[8:11]
	v_mfma_f32_16x16x32_bf16 v[4:7], v[226:229], v[218:221], v[4:7]
	v_mfma_f32_16x16x32_bf16 v[0:3], v[234:237], v[218:221], v[0:3]
	v_mfma_f32_16x16x32_bf16 v[28:31], v[230:233], v[194:197], v[28:31]
	v_mfma_f32_16x16x32_bf16 v[24:27], v[238:241], v[194:197], v[24:27]
	v_mfma_f32_16x16x32_bf16 v[20:23], v[230:233], v[202:205], v[20:23]
	v_mfma_f32_16x16x32_bf16 v[16:19], v[238:241], v[202:205], v[16:19]
	v_mfma_f32_16x16x32_bf16 v[12:15], v[230:233], v[214:217], v[12:15]
	v_mfma_f32_16x16x32_bf16 v[8:11], v[238:241], v[214:217], v[8:11]
	v_mfma_f32_16x16x32_bf16 v[4:7], v[230:233], v[222:225], v[4:7]
	v_mfma_f32_16x16x32_bf16 v[0:3], v[238:241], v[222:225], v[0:3]
	s_add_i32 s14, s14, 2
	v_lshl_add_u64 v[144:145], v[144:145], 0, s[20:21]
	v_lshl_add_u64 v[146:147], v[146:147], 0, s[20:21]
	v_lshl_add_u64 v[148:149], v[148:149], 0, s[20:21]
	s_cmp_lt_u32 s14, 4
	v_lshl_add_u64 v[150:151], v[150:151], 0, s[20:21]
	s_barrier
	s_cbranch_scc1 .LBB0_1204
	s_add_u32 s14, s46, 0x160380
	s_addc_u32 s15, s47, 0
	v_lshl_add_u64 v[142:143], s[14:15], 0, v[142:143]
	v_readfirstlane_b32 s18, v176
	v_lshl_add_u64 v[128:129], v[128:129], 1, v[142:143]
	s_mov_b32 m0, s18
	ds_read_b128 v[136:139], v175
	ds_read_b128 v[144:147], v175 offset:1024
	ds_read_b128 v[148:151], v175 offset:2048
	ds_read_b128 v[168:171], v175 offset:3072
	ds_read_b128 v[178:181], v160
	ds_read_b128 v[182:185], v160 offset:1024
	ds_read_b128 v[186:189], v159
	ds_read_b128 v[190:193], v159 offset:1024
	ds_read_b128 v[194:197], v158
	ds_read_b128 v[198:201], v158 offset:1024
	ds_read_b128 v[202:205], v157
	ds_read_b128 v[208:211], v157 offset:1024
	global_load_lds_dwordx4 v[128:129], off
	v_lshl_add_u64 v[128:129], s[14:15], 0, v[140:141]
	v_readfirstlane_b32 s14, v177
	v_lshl_add_u64 v[128:129], v[130:131], 1, v[128:129]
	s_mov_b32 m0, s14
	s_nop 0
	global_load_lds_dwordx4 v[128:129], off
	s_barrier
	s_waitcnt lgkmcnt(0)
	s_waitcnt lgkmcnt(0)
	v_mfma_f32_16x16x32_bf16 v[124:127], v[136:139], v[178:181], v[124:127]
	v_mfma_f32_16x16x32_bf16 v[120:123], v[148:151], v[178:181], v[120:123]
	v_mfma_f32_16x16x32_bf16 v[116:119], v[136:139], v[186:189], v[116:119]
	v_mfma_f32_16x16x32_bf16 v[112:115], v[148:151], v[186:189], v[112:115]
	v_mfma_f32_16x16x32_bf16 v[108:111], v[136:139], v[194:197], v[108:111]
	v_mfma_f32_16x16x32_bf16 v[104:107], v[148:151], v[194:197], v[104:107]
	v_mfma_f32_16x16x32_bf16 v[100:103], v[136:139], v[202:205], v[100:103]
	v_mfma_f32_16x16x32_bf16 v[96:99], v[148:151], v[202:205], v[96:99]
	v_mfma_f32_16x16x32_bf16 v[124:127], v[144:147], v[182:185], v[124:127]
	v_mfma_f32_16x16x32_bf16 v[120:123], v[168:171], v[182:185], v[120:123]
	v_mfma_f32_16x16x32_bf16 v[116:119], v[144:147], v[190:193], v[116:119]
	v_mfma_f32_16x16x32_bf16 v[112:115], v[168:171], v[190:193], v[112:115]
	v_mfma_f32_16x16x32_bf16 v[108:111], v[144:147], v[198:201], v[108:111]
	v_mfma_f32_16x16x32_bf16 v[104:107], v[168:171], v[198:201], v[104:107]
	v_mfma_f32_16x16x32_bf16 v[100:103], v[144:147], v[208:211], v[100:103]
	v_mfma_f32_16x16x32_bf16 v[96:99], v[168:171], v[208:211], v[96:99]
	s_barrier
	ds_read_b128 v[128:131], v173
	ds_read_b128 v[140:143], v173 offset:1024
	ds_read_b128 v[174:177], v173 offset:2048
	ds_read_b128 v[214:217], v173 offset:3072
	s_barrier
; #define STAGE(P, BASE, br, kt) STAGET(tid_, P, BASE, br, kt)
; #define LDA(dst, b, h) UFOR(m, 4) UFOR(k, 2) \
;     dst[m][k] = *reinterpret_cast<const bf16x8*>((char*)SA(b, h) + lds_byte(wr * 64 + m * 16 + fr, k * 32 + fq * 8))
; #define LDB(dst, b, h) UFOR(n, 2) UFOR(k, 2) \
;     dst[n][k] = *reinterpret_cast<const bf16x8*>((char*)SB(b, h) + lds_byte(wc * 32 + n * 16 + fr, k * 32 + fq * 8))
; #define MMA(ai, bj, At, Bq) do { __builtin_amdgcn_s_setprio(1); \
;     UFOR(m, 4) UFOR(n, 2) UFOR(k, 2) \
;       acc[ai][bj][m][n] = __builtin_amdgcn_mfma_f32_16x16x32_bf16(Bq[n][k], At[m][k], acc[ai][bj][m][n], 0, 0, 0); \
;     __builtin_amdgcn_s_setprio(0); } while (0)
; #define WAIT_V(n) asm volatile("s_waitcnt vmcnt(" #n ")" ::: "memory")
; #define WAIT_L(n) asm volatile("s_waitcnt lgkmcnt(" #n ")" ::: "memory")
; #define BAR __builtin_amdgcn_s_barrier()
; template <int EPI, int K, int KL> ...
;     ...
;   { LDB(B0, 0, 0); LDA(At, 0, 0); STAGE(SA(1, 1), A, brow + HALF, nt - 1);
;     BAR; WAIT_L(0); MMA(0, 0, At, B0); BAR;
;     LDB(B1, 0, 1); BAR; WAIT_L(0); MMA(0, 1, At, B1); BAR;
;     LDA(At, 0, 1); WAIT_V(4); BAR; WAIT_L(0); MMA(1, 0, At, B0); MMA(1, 1, At, B1); BAR; }
;   { LDB(B0, 1, 0); LDA(At, 1, 0); WAIT_V(2); BAR; WAIT_L(0); MMA(0, 0, At, B0); BAR;
;     LDB(B1, 1, 1); WAIT_V(0); BAR; WAIT_L(0); MMA(0, 1, At, B1); BAR;
;     LDA(At, 1, 1); BAR; WAIT_L(0); MMA(1, 0, At, B0); MMA(1, 1, At, B1); BAR; }
;   if (wr == 0) BAR;
	s_waitcnt lgkmcnt(0)
	s_waitcnt lgkmcnt(0)
	v_mfma_f32_16x16x32_bf16 v[92:95], v[128:131], v[178:181], v[92:95]
	v_mfma_f32_16x16x32_bf16 v[88:91], v[174:177], v[178:181], v[88:91]
	v_mfma_f32_16x16x32_bf16 v[84:87], v[128:131], v[186:189], v[84:87]
	v_mfma_f32_16x16x32_bf16 v[80:83], v[174:177], v[186:189], v[80:83]
	v_mfma_f32_16x16x32_bf16 v[76:79], v[128:131], v[194:197], v[76:79]
	v_mfma_f32_16x16x32_bf16 v[68:71], v[128:131], v[202:205], v[68:71]
	v_mfma_f32_16x16x32_bf16 v[64:67], v[174:177], v[202:205], v[64:67]
	v_mfma_f32_16x16x32_bf16 v[92:95], v[140:143], v[182:185], v[92:95]
	v_mfma_f32_16x16x32_bf16 v[88:91], v[214:217], v[182:185], v[88:91]
	v_mfma_f32_16x16x32_bf16 v[84:87], v[140:143], v[190:193], v[84:87]
	v_mfma_f32_16x16x32_bf16 v[80:83], v[214:217], v[190:193], v[80:83]
	v_mfma_f32_16x16x32_bf16 v[76:79], v[140:143], v[198:201], v[76:79]
	v_mfma_f32_16x16x32_bf16 v[72:75], v[174:177], v[194:197], v[72:75]
	v_mfma_f32_16x16x32_bf16 v[68:71], v[140:143], v[208:211], v[68:71]
	v_mfma_f32_16x16x32_bf16 v[64:67], v[214:217], v[208:211], v[64:67]
	v_mfma_f32_16x16x32_bf16 v[178:181], v[214:217], v[198:201], v[72:75]
	s_barrier
	s_nop 3
	ds_read_b128 v[72:75], v160 offset:16384
	ds_read_b128 v[182:185], v160 offset:17408
	ds_read_b128 v[186:189], v159 offset:16384
	ds_read_b128 v[190:193], v159 offset:17408
	ds_read_b128 v[194:197], v158 offset:16384
	ds_read_b128 v[198:201], v158 offset:17408
	ds_read_b128 v[202:205], v157 offset:16384
	ds_read_b128 v[208:211], v157 offset:17408
	s_waitcnt vmcnt(4)
	s_barrier
	s_waitcnt lgkmcnt(0)
	s_waitcnt lgkmcnt(0)
	v_mfma_f32_16x16x32_bf16 v[48:51], v[148:151], v[186:189], v[48:51]
	v_mfma_f32_16x16x32_bf16 v[60:63], v[136:139], v[72:75], v[60:63]
	v_mfma_f32_16x16x32_bf16 v[56:59], v[148:151], v[72:75], v[56:59]
	v_mfma_f32_16x16x32_bf16 v[52:55], v[136:139], v[186:189], v[52:55]
	v_mfma_f32_16x16x32_bf16 v[48:51], v[168:171], v[190:193], v[48:51]
	v_mfma_f32_16x16x32_bf16 v[44:47], v[136:139], v[194:197], v[44:47]
	v_mfma_f32_16x16x32_bf16 v[40:43], v[148:151], v[194:197], v[40:43]
	v_mfma_f32_16x16x32_bf16 v[36:39], v[136:139], v[202:205], v[36:39]
	v_mfma_f32_16x16x32_bf16 v[32:35], v[148:151], v[202:205], v[32:35]
	v_mfma_f32_16x16x32_bf16 v[218:221], v[144:147], v[182:185], v[60:63]
	v_mfma_f32_16x16x32_bf16 v[222:225], v[168:171], v[182:185], v[56:59]
	v_mfma_f32_16x16x32_bf16 v[226:229], v[144:147], v[190:193], v[52:55]
	v_mfma_f32_16x16x32_bf16 v[230:233], v[144:147], v[198:201], v[44:47]
	v_mfma_f32_16x16x32_bf16 v[234:237], v[168:171], v[198:201], v[40:43]
	v_mfma_f32_16x16x32_bf16 v[136:139], v[144:147], v[208:211], v[36:39]
	v_mfma_f32_16x16x32_bf16 v[144:147], v[168:171], v[208:211], v[32:35]
	v_mfma_f32_16x16x32_bf16 v[28:31], v[128:131], v[72:75], v[28:31]
	v_mfma_f32_16x16x32_bf16 v[24:27], v[174:177], v[72:75], v[24:27]
	v_mfma_f32_16x16x32_bf16 v[20:23], v[128:131], v[186:189], v[20:23]
	v_mfma_f32_16x16x32_bf16 v[16:19], v[174:177], v[186:189], v[16:19]
	v_mfma_f32_16x16x32_bf16 v[12:15], v[128:131], v[194:197], v[12:15]
	v_mfma_f32_16x16x32_bf16 v[8:11], v[174:177], v[194:197], v[8:11]
	v_mfma_f32_16x16x32_bf16 v[4:7], v[128:131], v[202:205], v[4:7]
	v_mfma_f32_16x16x32_bf16 v[0:3], v[174:177], v[202:205], v[0:3]
	v_mfma_f32_16x16x32_bf16 v[148:151], v[140:143], v[182:185], v[28:31]
	v_mfma_f32_16x16x32_bf16 v[168:171], v[214:217], v[182:185], v[24:27]
	v_mfma_f32_16x16x32_bf16 v[182:185], v[140:143], v[190:193], v[20:23]
	v_mfma_f32_16x16x32_bf16 v[186:189], v[214:217], v[190:193], v[16:19]
	v_mfma_f32_16x16x32_bf16 v[190:193], v[140:143], v[198:201], v[12:15]
	v_mfma_f32_16x16x32_bf16 v[194:197], v[214:217], v[198:201], v[8:11]
	v_mfma_f32_16x16x32_bf16 v[128:131], v[140:143], v[208:211], v[4:7]
	v_mfma_f32_16x16x32_bf16 v[140:143], v[214:217], v[208:211], v[0:3]
	s_barrier
	ds_read_b128 v[172:175], v166
	ds_read_b128 v[198:201], v166 offset:1024
	ds_read_b128 v[202:205], v166 offset:2048
	ds_read_b128 v[164:167], v166 offset:3072
	ds_read_b128 v[20:23], v160 offset:32768
	ds_read_b128 v[24:27], v160 offset:33792
	ds_read_b128 v[28:31], v159 offset:32768
	ds_read_b128 v[32:35], v159 offset:33792
	ds_read_b128 v[36:39], v158 offset:32768
	ds_read_b128 v[208:211], v158 offset:33792
	ds_read_b128 v[214:217], v157 offset:32768
	ds_read_b128 v[238:241], v157 offset:33792
	s_waitcnt vmcnt(2)
	s_barrier
; #define STAGE(P, BASE, br, kt) STAGET(tid_, P, BASE, br, kt)
; #define LDA(dst, b, h) UFOR(m, 4) UFOR(k, 2) \
;     dst[m][k] = *reinterpret_cast<const bf16x8*>((char*)SA(b, h) + lds_byte(wr * 64 + m * 16 + fr, k * 32 + fq * 8))
; #define LDB(dst, b, h) UFOR(n, 2) UFOR(k, 2) \
;     dst[n][k] = *reinterpret_cast<const bf16x8*>((char*)SB(b, h) + lds_byte(wc * 32 + n * 16 + fr, k * 32 + fq * 8))
; #define MMA(ai, bj, At, Bq) do { __builtin_amdgcn_s_setprio(1); \
;     UFOR(m, 4) UFOR(n, 2) UFOR(k, 2) \
;       acc[ai][bj][m][n] = __builtin_amdgcn_mfma_f32_16x16x32_bf16(Bq[n][k], At[m][k], acc[ai][bj][m][n], 0, 0, 0); \
;     __builtin_amdgcn_s_setprio(0); } while (0)
; #define WAIT_V(n) asm volatile("s_waitcnt vmcnt(" #n ")" ::: "memory")
; #define WAIT_L(n) asm volatile("s_waitcnt lgkmcnt(" #n ")" ::: "memory")
; #define BAR __builtin_amdgcn_s_barrier()
; template <int EPI, int K, int KL> ...
;     ...
;   { LDB(B0, 0, 0); LDA(At, 0, 0); STAGE(SA(1, 1), A, brow + HALF, nt - 1);
;     BAR; WAIT_L(0); MMA(0, 0, At, B0); BAR;
;     LDB(B1, 0, 1); BAR; WAIT_L(0); MMA(0, 1, At, B1); BAR;
;     LDA(At, 0, 1); WAIT_V(4); BAR; WAIT_L(0); MMA(1, 0, At, B0); MMA(1, 1, At, B1); BAR; }
;   { LDB(B0, 1, 0); LDA(At, 1, 0); WAIT_V(2); BAR; WAIT_L(0); MMA(0, 0, At, B0); BAR;
;     LDB(B1, 1, 1); WAIT_V(0); BAR; WAIT_L(0); MMA(0, 1, At, B1); BAR;
;     LDA(At, 1, 1); BAR; WAIT_L(0); MMA(1, 0, At, B0); MMA(1, 1, At, B1); BAR; }
;   if (wr == 0) BAR;
	s_waitcnt lgkmcnt(0)
	s_waitcnt lgkmcnt(0)
	v_mfma_f32_16x16x32_bf16 v[0:3], v[172:175], v[20:23], v[124:127]
	v_mfma_f32_16x16x32_bf16 v[44:47], v[198:201], v[24:27], v[0:3]
	v_mfma_f32_16x16x32_bf16 v[0:3], v[202:205], v[20:23], v[120:123]
	v_mfma_f32_16x16x32_bf16 v[52:55], v[164:167], v[24:27], v[0:3]
	v_mfma_f32_16x16x32_bf16 v[0:3], v[172:175], v[28:31], v[116:119]
	v_mfma_f32_16x16x32_bf16 v[40:43], v[198:201], v[32:35], v[0:3]
	v_mfma_f32_16x16x32_bf16 v[0:3], v[202:205], v[28:31], v[112:115]
	v_mfma_f32_16x16x32_bf16 v[16:19], v[164:167], v[32:35], v[0:3]
	v_mfma_f32_16x16x32_bf16 v[0:3], v[172:175], v[36:39], v[108:111]
	v_mfma_f32_16x16x32_bf16 v[8:11], v[198:201], v[208:211], v[0:3]
	v_mfma_f32_16x16x32_bf16 v[0:3], v[202:205], v[36:39], v[104:107]
	v_mfma_f32_16x16x32_bf16 v[12:15], v[164:167], v[208:211], v[0:3]
	v_mfma_f32_16x16x32_bf16 v[0:3], v[172:175], v[214:217], v[100:103]
	v_mfma_f32_16x16x32_bf16 v[4:7], v[202:205], v[214:217], v[96:99]
	v_mfma_f32_16x16x32_bf16 v[0:3], v[198:201], v[238:241], v[0:3]
	v_mfma_f32_16x16x32_bf16 v[4:7], v[164:167], v[238:241], v[4:7]
	s_barrier
	ds_read_b128 v[108:111], v163
	ds_read_b128 v[242:245], v163 offset:1024
	ds_read_b128 v[246:249], v163 offset:2048
	ds_read_b128 v[152:155], v163 offset:3072
	s_waitcnt vmcnt(0)
	s_barrier
	s_waitcnt lgkmcnt(0)
	s_waitcnt lgkmcnt(0)
	v_mfma_f32_16x16x32_bf16 v[56:59], v[108:111], v[20:23], v[92:95]
	v_mfma_f32_16x16x32_bf16 v[20:23], v[246:249], v[20:23], v[88:91]
	v_mfma_f32_16x16x32_bf16 v[72:75], v[152:155], v[24:27], v[20:23]
	v_mfma_f32_16x16x32_bf16 v[20:23], v[108:111], v[28:31], v[84:87]
	v_mfma_f32_16x16x32_bf16 v[60:63], v[242:245], v[24:27], v[56:59]
	v_mfma_f32_16x16x32_bf16 v[56:59], v[242:245], v[32:35], v[20:23]
	v_mfma_f32_16x16x32_bf16 v[20:23], v[246:249], v[28:31], v[80:83]
	v_mfma_f32_16x16x32_bf16 v[20:23], v[152:155], v[32:35], v[20:23]
	v_mfma_f32_16x16x32_bf16 v[24:27], v[108:111], v[36:39], v[76:79]
	v_mfma_f32_16x16x32_bf16 v[28:31], v[246:249], v[36:39], v[178:181]
	v_mfma_f32_16x16x32_bf16 v[32:35], v[108:111], v[214:217], v[68:71]
	v_mfma_f32_16x16x32_bf16 v[36:39], v[246:249], v[214:217], v[64:67]
	v_mfma_f32_16x16x32_bf16 v[24:27], v[242:245], v[208:211], v[24:27]
	v_mfma_f32_16x16x32_bf16 v[28:31], v[152:155], v[208:211], v[28:31]
	v_mfma_f32_16x16x32_bf16 v[32:35], v[242:245], v[238:241], v[32:35]
	v_mfma_f32_16x16x32_bf16 v[36:39], v[152:155], v[238:241], v[36:39]
	s_barrier
	ds_read_b128 v[88:91], v160 offset:49152
	ds_read_b128 v[92:95], v160 offset:50176
	ds_read_b128 v[96:99], v159 offset:49152
	ds_read_b128 v[100:103], v159 offset:50176
	ds_read_b128 v[104:107], v158 offset:49152
	ds_read_b128 v[158:161], v158 offset:50176
	ds_read_b128 v[176:179], v157 offset:49152
	ds_read_b128 v[208:211], v157 offset:50176
	s_barrier
	s_waitcnt lgkmcnt(0)
	s_waitcnt lgkmcnt(0)
	v_mfma_f32_16x16x32_bf16 v[48:51], v[202:205], v[96:99], v[48:51]
	v_mfma_f32_16x16x32_bf16 v[64:67], v[172:175], v[88:91], v[218:221]
	v_mfma_f32_16x16x32_bf16 v[116:119], v[164:167], v[100:103], v[48:51]
	v_mfma_f32_16x16x32_bf16 v[48:51], v[172:175], v[104:107], v[230:233]
	v_mfma_f32_16x16x32_bf16 v[120:123], v[198:201], v[92:95], v[64:67]
	v_mfma_f32_16x16x32_bf16 v[64:67], v[202:205], v[88:91], v[222:225]
	v_mfma_f32_16x16x32_bf16 v[76:79], v[198:201], v[158:161], v[48:51]
	v_mfma_f32_16x16x32_bf16 v[48:51], v[202:205], v[104:107], v[234:237]
	v_mfma_f32_16x16x32_bf16 v[124:127], v[164:167], v[92:95], v[64:67]
	v_mfma_f32_16x16x32_bf16 v[64:67], v[172:175], v[96:99], v[226:229]
	v_mfma_f32_16x16x32_bf16 v[80:83], v[164:167], v[158:161], v[48:51]
	v_mfma_f32_16x16x32_bf16 v[48:51], v[172:175], v[176:179], v[136:139]
	v_mfma_f32_16x16x32_bf16 v[112:115], v[198:201], v[100:103], v[64:67]
	v_mfma_f32_16x16x32_bf16 v[64:67], v[198:201], v[208:211], v[48:51]
	v_mfma_f32_16x16x32_bf16 v[48:51], v[202:205], v[176:179], v[144:147]
	v_mfma_f32_16x16x32_bf16 v[68:71], v[164:167], v[208:211], v[48:51]
	v_mfma_f32_16x16x32_bf16 v[48:51], v[108:111], v[88:91], v[148:151]
	v_mfma_f32_16x16x32_bf16 v[84:87], v[242:245], v[92:95], v[48:51]
	v_mfma_f32_16x16x32_bf16 v[48:51], v[246:249], v[88:91], v[168:171]
	v_mfma_f32_16x16x32_bf16 v[88:91], v[152:155], v[92:95], v[48:51]
	v_mfma_f32_16x16x32_bf16 v[48:51], v[108:111], v[96:99], v[182:185]
	v_mfma_f32_16x16x32_bf16 v[92:95], v[242:245], v[100:103], v[48:51]
	v_mfma_f32_16x16x32_bf16 v[48:51], v[246:249], v[96:99], v[186:189]
	v_mfma_f32_16x16x32_bf16 v[96:99], v[152:155], v[100:103], v[48:51]
	v_mfma_f32_16x16x32_bf16 v[48:51], v[108:111], v[104:107], v[190:193]
	v_mfma_f32_16x16x32_bf16 v[100:103], v[242:245], v[158:161], v[48:51]
	v_mfma_f32_16x16x32_bf16 v[48:51], v[246:249], v[104:107], v[194:197]
	v_mfma_f32_16x16x32_bf16 v[104:107], v[152:155], v[158:161], v[48:51]
	v_mfma_f32_16x16x32_bf16 v[48:51], v[108:111], v[176:179], v[128:131]
	v_mfma_f32_16x16x32_bf16 v[108:111], v[242:245], v[208:211], v[48:51]
	v_mfma_f32_16x16x32_bf16 v[48:51], v[246:249], v[176:179], v[140:143]
	v_mfma_f32_16x16x32_bf16 v[48:51], v[152:155], v[208:211], v[48:51]
	s_movk_i32 s14, 0x100
	v_cmp_gt_u32_e32 vcc, s14, v132
	s_barrier
	s_and_saveexec_b64 s[44:45], vcc
	s_cbranch_execz .LBB0_1200
	s_barrier
	s_branch .LBB0_1200
